# S
# speedup vs baseline: 1.0002x; 1.0002x over previous
; template <int MODE> ...
;   int tid = threadIdx.x;
;   asm volatile("" : "+v"(tid));
;   const int lane = tid & 63, c = lane & 15, quad = lane >> 4;
;   float m_run[2] = {-1e30f, -1e30f}, l_run[2] = {0.f, 0.f};
; #pragma unroll
;   for (int qs = 0; qs < 2; ++qs)
; #pragma unroll
;     for (int i = 0; i < 8; ++i) o[qs][i] = (f32x4){0.f, 0.f, 0.f, 0.f};
;   const int krow0 = tid >> 4, kch = tid & 15;
;   const int vrow0 = tid >> 3, vch = tid & 7;
;   const bf16_t* kp = Kg + (size_t)(jlo * 64 + krow0) * NPAD + kch * 8;
;   const bf16_t* vp0 = VTg + (size_t)vrow0 * SEQ + jlo * 64 + vch * 8;
;   uint4 kr0 = *(const uint4*)kp, kr1 = *(const uint4*)(kp + (size_t)32 * NPAD);
;   uint4 vr0 = *(const uint4*)vp0, vr1 = *(const uint4*)(vp0 + (size_t)64 * SEQ);
;   __syncthreads();
;   stage_write_k((bf16_t*)smem, krow0, kch, kr0, kr1);
;   stage_write_v((bf16_t*)(smem + KT_BYTES), vrow0, vch, vr0, vr1);
;   __syncthreads();
; __device__ __forceinline__ void attn_phase(const bf16_t* __restrict__ proj, const bf16_t* __restrict__ KC,
;                            const bf16_t* __restrict__ VCT, const bf16_t* __restrict__ VT,
;                            bf16_t* __restrict__ mixed) {
;     ...
;     bf16x8 qf[2][4];
; #pragma unroll
;     for (int qs = 0; qs < 2; ++qs) {
;       const bf16_t* qp = proj + (row0 + qs * 4) * NPAD + OFF_Q + head * 128 + quad * 8;
; #pragma unroll
;       for (int ks = 0; ks < 4; ++ks) qf[qs][ks] = *(const bf16x8*)(qp + ks * 32);
;     }
.LBB0_319:
	v_mov_b64_e32 v[0:1], s[36:37]
	v_mad_u64_u32 v[192:193], s[8:9], v184, s81, v[0:1]
	v_mad_i32_i24 v193, v185, s81, v193
	s_mul_i32 s8, s34, 0x7a00
	v_mov_b32_e32 v105, v181
	v_lshl_add_u64 v[0:1], v[192:193], 0, v[180:181]
	s_add_u32 s25, s36, s8
	v_lshl_add_u64 v[16:17], v[0:1], 0, v[104:105]
	s_addc_u32 s60, s37, 0
	s_lshl_b32 s9, s24, 8
	v_add_co_u32_e32 v8, vcc, s47, v16
	s_add_u32 s10, s25, s9
	s_nop 0
	v_addc_co_u32_e32 v9, vcc, 0, v17, vcc
	s_addc_u32 s11, s60, 0
	v_add_co_u32_e32 v24, vcc, s85, v16
	s_add_u32 s10, s10, 0x5800
	v_lshl_add_u64 v[12:13], v[16:17], 0, s[40:41]
	v_lshl_add_u64 v[28:29], v[16:17], 0, s[44:45]
	v_addc_co_u32_e32 v25, vcc, 0, v17, vcc
	s_addc_u32 s11, s11, 0
	s_lshl_b32 s12, s95, 20
	v_mov_b32_e32 v39, v254
	global_load_dwordx4 v[0:3], v[12:13], off offset:64
	global_load_dwordx4 v[4:7], v[12:13], off offset:128
	s_nop 0
	global_load_dwordx4 v[8:11], v[8:9], off
	s_nop 0
	global_load_dwordx4 v[12:15], v[12:13], off offset:192
	s_nop 0
	global_load_dwordx4 v[16:19], v[28:29], off offset:64
	global_load_dwordx4 v[20:23], v[28:29], off offset:128
	s_nop 0
	global_load_dwordx4 v[24:27], v[24:25], off offset:2048
	s_nop 0
	global_load_dwordx4 v[28:31], v[28:29], off offset:192
	s_and_b32 s12, s12, 0x700000
	v_mov_b64_e32 v[32:33], s[10:11]
	v_and_b32_e32 v172, 15, v39
	v_ashrrev_i32_e32 v38, 4, v39
	v_ashrrev_i32_e32 v56, 3, v39
	s_add_u32 s14, s75, s12
	v_mad_i64_i32 v[34:35], s[10:11], v38, s81, v[32:33]
	v_lshlrev_b32_e32 v32, 4, v172
	v_mov_b32_e32 v33, v181
	v_ashrrev_i32_e32 v57, 31, v56
	s_addc_u32 s15, s76, 0
	v_and_b32_e32 v36, 7, v39
	v_lshl_add_u64 v[48:49], v[34:35], 0, v[32:33]
	v_lshlrev_b64 v[34:35], 13, v[56:57]
	v_lshl_add_u64 v[40:41], s[14:15], 0, v[34:35]
	v_lshlrev_b32_e32 v36, 4, v36
	v_mov_b32_e32 v37, v181
	v_lshl_add_u64 v[52:53], v[40:41], 0, v[36:37]
	global_load_dwordx4 v[40:43], v[52:53], off
	global_load_dwordx4 v[44:47], v[48:49], off
	v_add_co_u32_e32 v48, vcc, s89, v48
	v_bfe_u32 v170, v39, 4, 2
	s_nop 0
	v_addc_co_u32_e32 v49, vcc, 0, v49, vcc
	global_load_dwordx4 v[48:51], v[48:49], off
	v_add_co_u32_e32 v52, vcc, s88, v52
	v_lshlrev_b32_e32 v57, 3, v39
	s_nop 0
	v_addc_co_u32_e32 v53, vcc, 0, v53, vcc
	global_load_dwordx4 v[52:55], v[52:53], off
	v_lshlrev_b32_e32 v58, 4, v39
	v_lshlrev_b32_e32 v39, 1, v39
	v_and_b32_e32 v57, 32, v57
	v_and_b32_e32 v58, 16, v58
	v_and_b32_e32 v39, 4, v39
	v_mul_lo_u32 v59, v38, s86
	v_mul_lo_u32 v56, v56, s87
	v_or3_b32 v39, v57, v58, v39
	v_lshlrev_b32_e32 v173, 1, v59
	v_lshlrev_b32_e32 v174, 1, v56
	v_lshlrev_b32_e32 v175, 1, v39
	v_lshrrev_b32_e32 v58, 5, v254
	v_lshrrev_b32_e32 v59, 6, v254
	v_xor_b32_e32 v58, v58, v59
	v_and_b32_e32 v58, 1, v58
	v_lshlrev_b32_e32 v58, 4, v58
	v_add_u32_e32 v175, v175, v58
	v_add3_u32 v56, 16, v173, v32
	v_lshrrev_b32_e32 v58, 6, v254
	v_lshrrev_b32_e32 v59, 7, v254
	v_xor_b32_e32 v58, v58, v59
	v_and_b32_e32 v58, 1, v58
	v_bfe_u32 v59, v254, 0, 1
	v_and_b32_e32 v59, v59, v58
	v_lshlrev_b32_e32 v58, 4, v58
	v_lshlrev_b32_e32 v59, 5, v59
	v_sub_u32_e32 v58, v58, v59
	v_add_u32_e32 v56, v56, v58
	v_add3_u32 v39, 16, v174, v175
	v_xor_b32_e32 v59, 16, v175
	v_add3_u32 v58, 16, v174, v59
	s_cmp_lg_u32 s96, 0
	v_lshlrev_b32_e32 v171, 4, v170
	v_add_u32_e32 v57, 0x4000, v39
	v_add_u32_e32 v39, 0x6800, v39
	s_barrier
	s_waitcnt vmcnt(2)
	ds_write_b128 v56, v[44:47]
	s_waitcnt vmcnt(1)
	ds_write_b128 v56, v[48:51] offset:8704
	ds_write_b64 v57, v[40:41] offset:1024
	ds_write_b64 v58, v[42:43] offset:17408
	s_waitcnt vmcnt(0)
	ds_write_b64 v39, v[52:53]
	ds_write_b64 v58, v[54:55] offset:26624
	s_waitcnt lgkmcnt(0)
	s_barrier
	s_cbranch_scc0 .LBB0_327
	s_add_u32 s8, s9, s8
	v_mad_i64_i32 v[38:39], s[10:11], v38, s81, 0
	s_addc_u32 s9, 0, 0
	v_lshl_add_u64 v[38:39], s[8:9], 0, v[38:39]
	s_and_b32 s8, s95, 7
	s_lshl_b32 s34, s8, 20
	v_lshlrev_b32_e32 v40, 3, v172
	v_lshl_add_u64 v[144:145], v[38:39], 0, v[32:33]
	v_lshl_add_u64 v[32:33], s[34:35], 0, v[34:35]
	v_mov_b32_e32 v48, v181
	v_mov_b32_e32 v49, v181
	v_mov_b32_e32 v50, v181
	v_mov_b32_e32 v51, v181
	v_lshl_add_u64 v[146:147], v[32:33], 0, v[36:37]
	v_mov_b32_e32 v164, 0xf149f2ca
	v_lshlrev_b32_e32 v179, 1, v40
	v_lshrrev_b32_e32 v96, 6, v254
	v_lshrrev_b32_e32 v97, 7, v254
	v_xor_b32_e32 v96, v96, v97
	v_and_b32_e32 v96, 1, v96
	v_bfe_u32 v97, v254, 0, 1
	v_and_b32_e32 v97, v97, v96
	v_lshlrev_b32_e32 v96, 4, v96
	v_lshlrev_b32_e32 v97, 5, v97
	v_sub_u32_e32 v96, v96, v97
	v_add_u32_e32 v179, v179, v96
	v_mov_b64_e32 v[32:33], v[48:49]
	v_mov_b64_e32 v[40:41], v[48:49]
	v_mov_b64_e32 v[54:55], v[50:51]
	v_mov_b64_e32 v[66:67], v[50:51]
	v_mov_b64_e32 v[74:75], v[50:51]
	v_mov_b64_e32 v[82:83], v[50:51]
	v_mov_b64_e32 v[90:91], v[50:51]
	v_mov_b64_e32 v[62:63], v[50:51]
	v_mov_b64_e32 v[36:37], v[48:49]
	v_mov_b64_e32 v[44:45], v[48:49]
	v_mov_b64_e32 v[58:59], v[50:51]
	v_mov_b64_e32 v[70:71], v[50:51]
	v_mov_b64_e32 v[78:79], v[50:51]
	v_mov_b64_e32 v[86:87], v[50:51]
	v_mov_b64_e32 v[94:95], v[50:51]
	v_mul_u32_u24_e32 v176, 0x110, v172
	v_mul_u32_u24_e32 v177, 0x90, v172
	v_add_u32_e32 v178, 16, v171
	v_lshrrev_b32_e32 v96, 2, v254
	v_lshrrev_b32_e32 v97, 3, v254
	v_xor_b32_e32 v96, v96, v97
	v_and_b32_e32 v96, 1, v96
	v_bfe_u32 v97, v254, 4, 1
	v_and_b32_e32 v97, v97, v96
	v_lshlrev_b32_e32 v96, 4, v96
	v_lshlrev_b32_e32 v97, 5, v97
	v_sub_u32_e32 v96, v96, v97
	v_add_u32_e32 v178, v178, v96
	v_mov_b32_e32 v194, v181
	v_mov_b32_e32 v195, v181
	s_mov_b64 s[58:59], 0
	v_mov_b64_e32 v[34:35], v[50:51]
	v_mov_b64_e32 v[42:43], v[50:51]
	v_mov_b64_e32 v[52:53], v[48:49]
	v_mov_b64_e32 v[64:65], v[48:49]
	v_mov_b64_e32 v[72:73], v[48:49]
	v_mov_b64_e32 v[80:81], v[48:49]
	v_mov_b64_e32 v[88:89], v[48:49]
	v_mov_b64_e32 v[60:61], v[48:49]
	v_mov_b64_e32 v[38:39], v[50:51]
	v_mov_b64_e32 v[46:47], v[50:51]
	v_mov_b64_e32 v[56:57], v[48:49]
	v_mov_b64_e32 v[68:69], v[48:49]
	v_mov_b64_e32 v[76:77], v[48:49]
	v_mov_b64_e32 v[84:85], v[48:49]
	v_mov_b64_e32 v[92:93], v[48:49]
	v_mov_b32_e32 v165, v164
	v_lshl_add_u64 v[144:145], s[30:31], 0, v[144:145]
	v_lshl_add_u64 v[146:147], s[30:31], 0, v[146:147]
	v_add_co_u32_e32 v144, vcc, s90, v144
	s_nop 1
	v_addc_co_u32_e32 v145, vcc, 0, v145, vcc
	v_add_co_u32_e32 v146, vcc, 0x3a800000, v146
	s_nop 1
	v_addc_co_u32_e32 v147, vcc, 0, v147, vcc
	s_branch .LBB0_323

; __device__ __forceinline__ void stage_write_v(bf16_t* Vt, int vrow0, int vch, uint4 vr0, uint4 vr1) {
;   const int g4a = 2 * vch, g4b = 2 * vch + 1;
;   const int pa = (g4a >> 3) * 32 + (g4a & 3) * 8 + ((g4a >> 2) & 1) * 4;
;   const int pb = (g4b >> 3) * 32 + (g4b & 3) * 8 + ((g4b >> 2) & 1) * 4;
;   *(uint2*)(Vt + vrow0 * VT_STRIDE + pa) = make_uint2(vr0.x, vr0.y);
;   *(uint2*)(Vt + vrow0 * VT_STRIDE + pb) = make_uint2(vr0.z, vr0.w);
;   *(uint2*)(Vt + (vrow0 + 64) * VT_STRIDE + pa) = make_uint2(vr1.x, vr1.y);
;   *(uint2*)(Vt + (vrow0 + 64) * VT_STRIDE + pb) = make_uint2(vr1.z, vr1.w);
; }
; template <int MODE> ...
;     ...
;     if (j < jhi) {
;       stage_write_k((bf16_t*)(smem + (cb ^ 1) * STAGE_BYTES), krow0, kch, kr0, kr1);
;       stage_write_v((bf16_t*)(smem + (cb ^ 1) * STAGE_BYTES + KT_BYTES), vrow0, vch, vr0, vr1);
;     }
;     __syncthreads();
.LBB0_322:
	s_xor_b32 s8, s34, 1
	s_mul_i32 s8, s8, 0x8c00
	s_add_i32 s8, s8, 16
	v_add3_u32 v112, s8, v173, v179
	s_add_u32 s58, s58, 1
	s_waitcnt vmcnt(3)
	ds_write_b128 v112, v[96:99]
	s_waitcnt vmcnt(2)
	ds_write_b128 v112, v[100:103] offset:8704
	v_add3_u32 v96, s8, v174, v175
	s_addc_u32 s59, s59, 0
	v_xor_b32_e32 v97, 16, v175
	v_add3_u32 v97, s8, v174, v97
	v_lshl_add_u64 v[144:145], v[144:145], 0, s[48:49]
	s_cmp_eq_u32 s96, s58
	v_lshl_add_u64 v[146:147], v[146:147], 0, s[50:51]
	s_waitcnt vmcnt(1)
	ds_write_b64 v96, v[104:105] offset:17408
	ds_write_b64 v97, v[106:107] offset:17408
	s_waitcnt vmcnt(0)
	ds_write_b64 v96, v[108:109] offset:26624
	ds_write_b64 v97, v[110:111] offset:26624
	s_waitcnt lgkmcnt(0)
	s_barrier
	s_cbranch_scc1 .LBB0_326

; template <int MODE> ...
;     ...
;     if (MODE == 0) need = (wunion >> j) & 1ull;
;     if (need) {
;       f32x4 s[2][4];
; #pragma unroll
;       for (int mt = 0; mt < 4; ++mt) {
;         s[0][mt] = (f32x4){0.f, 0.f, 0.f, 0.f};
;         s[1][mt] = (f32x4){0.f, 0.f, 0.f, 0.f};
;       }
; #pragma unroll
;       for (int ks = 0; ks < 4; ++ks)
; #pragma unroll
;         for (int mt = 0; mt < 4; ++mt) {
;           bf16x8 a = *(const bf16x8*)(Kt + (mt * 16 + c) * KT_STRIDE + ks * 32 + quad * 8);
;           s[0][mt] = __builtin_amdgcn_mfma_f32_16x16x32_bf16(a, qf[0][ks], s[0][mt], 0, 0, 0);
;           s[1][mt] = __builtin_amdgcn_mfma_f32_16x16x32_bf16(a, qf[1][ks], s[1][mt], 0, 0, 0);
;         }
;       const bool edge = (j == jhi) || (MODE == 1 && j == jhi - 8);
;       bf16x8 pb[2][2];
;       if (edge) {
; #pragma unroll
;         for (int qs = 0; qs < 2; ++qs) {
;           const int key0 = j * 64 + quad * 4;
;           const int tk = tok[qs];
; #pragma unroll
;           for (int mt = 0; mt < 4; ++mt)
; #pragma unroll
;             for (int jj = 0; jj < 4; ++jj) {
;               const int key = key0 + mt * 16 + jj;
;               bool valid = key <= tk;
;               if (MODE == 1) valid = valid && (key > tk - 512);
;               s[qs][mt][jj] = valid ? s[qs][mt][jj] : RAW_MASKED;
;             }
;         }
;       }
;       float alpha[2];
; #pragma unroll
;       for (int qs = 0; qs < 2; ++qs) {
;         const bool sel = (MODE == 1) ? true : (bool)((mymask[qs] >> j) & 1ull);
;         float mx4[4];
; #pragma unroll
;         for (int mt = 0; mt < 4; ++mt)
;           mx4[mt] = fmaxf(fmaxf(s[qs][mt][0], s[qs][mt][1]), fmaxf(s[qs][mt][2], s[qs][mt][3]));
;         float mx = fmaxf(fmaxf(mx4[0], mx4[1]), fmaxf(mx4[2], mx4[3]));
;         mx = sel ? mx * SCL : -1e30f;
;         mx = quad_max(mx);
.LBB0_330:
	s_lshl_b64 s[8:9], 1, s96
	s_and_b64 s[10:11], s[16:17], s[8:9]
	s_cmp_lg_u64 s[10:11], 0
	v_or_b32_e32 v198, 4, v186
	s_cbranch_scc0 .LBB0_345
	s_bitcmp1_b32 s96, 0
	s_cselect_b32 s10, 0x8c00, 0
	s_add_i32 s10, s10, 16
	v_add_u32_e32 v173, s10, v171
	v_lshrrev_b32_e32 v234, 2, v254
	v_lshrrev_b32_e32 v235, 3, v254
	v_xor_b32_e32 v234, v234, v235
	v_and_b32_e32 v234, 1, v234
	v_bfe_u32 v235, v254, 4, 1
	v_and_b32_e32 v235, v235, v234
	v_lshlrev_b32_e32 v234, 4, v234
	v_lshlrev_b32_e32 v235, 5, v235
	v_sub_u32_e32 v234, v234, v235
	v_add_u32_e32 v173, v173, v234
	v_mad_u32_u24 v171, v172, s78, v173
	ds_read_b128 v[166:169], v171
	ds_read_b128 v[234:237], v171 offset:64
	ds_read_b128 v[200:203], v171 offset:4352
	ds_read_b128 v[218:221], v171 offset:8704
	ds_read_b128 v[226:229], v171 offset:13056
	v_and_b32_e32 v163, s9, v163
	v_and_b32_e32 v162, s8, v162
	v_cmp_eq_u64_e64 s[10:11], 0, v[162:163]
	v_and_b32_e32 v161, s9, v161
	s_waitcnt lgkmcnt(4)
	v_mfma_f32_16x16x32_bf16 v[174:177], v[166:169], v[8:11], 0
	v_and_b32_e32 v160, s8, v160
	v_cmp_eq_u64_e64 s[8:9], 0, v[160:161]
	v_mfma_f32_16x16x32_bf16 v[166:169], v[166:169], v[24:27], 0
	s_waitcnt lgkmcnt(3)
	v_mfma_f32_16x16x32_bf16 v[174:177], v[234:237], v[0:3], v[174:177]
	v_mfma_f32_16x16x32_bf16 v[166:169], v[234:237], v[16:19], v[166:169]
	ds_read_b128 v[234:237], v171 offset:4416
	s_waitcnt lgkmcnt(3)
	v_mfma_f32_16x16x32_bf16 v[204:207], v[200:203], v[8:11], 0
	v_mfma_f32_16x16x32_bf16 v[200:203], v[200:203], v[24:27], 0
	s_waitcnt lgkmcnt(0)
	v_mfma_f32_16x16x32_bf16 v[204:207], v[234:237], v[0:3], v[204:207]
	v_mfma_f32_16x16x32_bf16 v[200:203], v[234:237], v[16:19], v[200:203]
	ds_read_b128 v[234:237], v171 offset:8768
	v_mfma_f32_16x16x32_bf16 v[222:225], v[218:221], v[8:11], 0
	v_mfma_f32_16x16x32_bf16 v[218:221], v[218:221], v[24:27], 0
	s_waitcnt lgkmcnt(0)
	v_mfma_f32_16x16x32_bf16 v[222:225], v[234:237], v[0:3], v[222:225]
	v_mfma_f32_16x16x32_bf16 v[218:221], v[234:237], v[16:19], v[218:221]
	ds_read_b128 v[234:237], v171 offset:13120
	v_mfma_f32_16x16x32_bf16 v[230:233], v[226:229], v[8:11], 0
	v_mfma_f32_16x16x32_bf16 v[226:229], v[226:229], v[24:27], 0
	s_waitcnt lgkmcnt(0)
	v_mfma_f32_16x16x32_bf16 v[230:233], v[234:237], v[0:3], v[230:233]
	v_mfma_f32_16x16x32_bf16 v[226:229], v[234:237], v[16:19], v[226:229]
	ds_read_b128 v[234:237], v171 offset:128
	s_waitcnt lgkmcnt(0)
	v_mfma_f32_16x16x32_bf16 v[174:177], v[234:237], v[4:7], v[174:177]
	v_mfma_f32_16x16x32_bf16 v[166:169], v[234:237], v[20:23], v[166:169]
	ds_read_b128 v[234:237], v171 offset:4480
	s_waitcnt lgkmcnt(0)
	v_mfma_f32_16x16x32_bf16 v[204:207], v[234:237], v[4:7], v[204:207]
	v_mfma_f32_16x16x32_bf16 v[200:203], v[234:237], v[20:23], v[200:203]
	ds_read_b128 v[234:237], v171 offset:8832
	s_waitcnt lgkmcnt(0)
	v_mfma_f32_16x16x32_bf16 v[222:225], v[234:237], v[4:7], v[222:225]
	v_mfma_f32_16x16x32_bf16 v[218:221], v[234:237], v[20:23], v[218:221]
	ds_read_b128 v[234:237], v171 offset:13184
	s_waitcnt lgkmcnt(0)
	v_mfma_f32_16x16x32_bf16 v[230:233], v[234:237], v[4:7], v[230:233]
	v_mfma_f32_16x16x32_bf16 v[226:229], v[234:237], v[20:23], v[226:229]
	ds_read_b128 v[234:237], v171 offset:192
	s_waitcnt lgkmcnt(0)
	v_mfma_f32_16x16x32_bf16 v[174:177], v[234:237], v[12:15], v[174:177]
	v_mfma_f32_16x16x32_bf16 v[234:237], v[234:237], v[28:31], v[166:169]
	s_nop 2
	ds_read_b128 v[166:169], v171 offset:4544
	s_waitcnt lgkmcnt(0)
	v_mfma_f32_16x16x32_bf16 v[204:207], v[166:169], v[12:15], v[204:207]
	v_mfma_f32_16x16x32_bf16 v[238:241], v[166:169], v[28:31], v[200:203]
	ds_read_b128 v[166:169], v171 offset:8896
	s_waitcnt lgkmcnt(0)
	v_mfma_f32_16x16x32_bf16 v[222:225], v[166:169], v[12:15], v[222:225]
	v_mfma_f32_16x16x32_bf16 v[242:245], v[166:169], v[28:31], v[218:221]
	ds_read_b128 v[166:169], v171 offset:13248
	s_waitcnt lgkmcnt(0)
	v_mfma_f32_16x16x32_bf16 v[230:233], v[166:169], v[12:15], v[230:233]
	v_mfma_f32_16x16x32_bf16 v[226:229], v[166:169], v[28:31], v[226:229]
	v_lshl_or_b32 v167, v170, 2, s97
	v_cmp_le_i32_e32 vcc, v167, v186
	v_or_b32_e32 v178, 18, v167
	v_or_b32_e32 v179, 19, v167
	v_cndmask_b32_e32 v168, v216, v174, vcc
	v_cmp_lt_i32_e32 vcc, v167, v186
	v_or_b32_e32 v174, 2, v167
	v_or_b32_e32 v183, 32, v167
	v_cndmask_b32_e32 v169, v216, v175, vcc
	v_cmp_le_i32_e32 vcc, v174, v186
	v_or_b32_e32 v175, 3, v167
	v_or_b32_e32 v191, 33, v167
	v_cndmask_b32_e32 v170, v216, v176, vcc
	v_cmp_le_i32_e32 vcc, v175, v186
	v_or_b32_e32 v176, 16, v167
	v_or_b32_e32 v196, 34, v167
	v_cndmask_b32_e32 v171, v216, v177, vcc
	v_cmp_le_i32_e32 vcc, v176, v186
	v_or_b32_e32 v177, 17, v167
	v_or_b32_e32 v197, 35, v167
	v_cndmask_b32_e32 v203, v216, v204, vcc
	v_cmp_le_i32_e32 vcc, v177, v186
	v_or_b32_e32 v199, 48, v167
	v_or_b32_e32 v200, 49, v167
	v_cndmask_b32_e32 v204, v216, v205, vcc
	v_cmp_le_i32_e32 vcc, v178, v186
	v_or_b32_e32 v201, 50, v167
	v_or_b32_e32 v202, 51, v167
	v_cndmask_b32_e32 v205, v216, v206, vcc
	v_cmp_le_i32_e32 vcc, v179, v186
	v_max_f32_e32 v208, v171, v171
	v_max_f32_e32 v209, v170, v170
	v_cndmask_b32_e32 v206, v216, v207, vcc
	v_cmp_le_i32_e32 vcc, v183, v186
	v_max_f32_e32 v208, v209, v208
	v_max_f32_e32 v209, v206, v206
	v_cndmask_b32_e32 v207, v216, v222, vcc
	v_cmp_le_i32_e32 vcc, v191, v186
	v_max3_f32 v208, v168, v169, v208
	s_nop 0
	v_cndmask_b32_e32 v217, v216, v223, vcc
	v_cmp_le_i32_e32 vcc, v196, v186
	s_nop 1
	v_cndmask_b32_e32 v218, v216, v224, vcc
	v_cmp_le_i32_e32 vcc, v197, v186
	v_max_f32_e32 v224, v205, v205
	v_max_f32_e32 v209, v224, v209
	v_cndmask_b32_e32 v219, v216, v225, vcc
	v_cmp_le_i32_e32 vcc, v199, v186
	v_max_f32_e32 v224, v217, v217
; template <int MODE> ...
;     ...
;       const bool edge = (j == jhi) || (MODE == 1 && j == jhi - 8);
;       bf16x8 pb[2][2];
;       if (edge) {
; #pragma unroll
;         for (int qs = 0; qs < 2; ++qs) {
;           const int key0 = j * 64 + quad * 4;
;           const int tk = tok[qs];
; #pragma unroll
;           for (int mt = 0; mt < 4; ++mt)
; #pragma unroll
;             for (int jj = 0; jj < 4; ++jj) {
;               const int key = key0 + mt * 16 + jj;
;               bool valid = key <= tk;
;               if (MODE == 1) valid = valid && (key > tk - 512);
;               s[qs][mt][jj] = valid ? s[qs][mt][jj] : RAW_MASKED;
;             }
;         }
;       }
;       float alpha[2];
; #pragma unroll
;       for (int qs = 0; qs < 2; ++qs) {
;         const bool sel = (MODE == 1) ? true : (bool)((mymask[qs] >> j) & 1ull);
;         float mx4[4];
; #pragma unroll
;         for (int mt = 0; mt < 4; ++mt)
;           mx4[mt] = fmaxf(fmaxf(s[qs][mt][0], s[qs][mt][1]), fmaxf(s[qs][mt][2], s[qs][mt][3]));
;         float mx = fmaxf(fmaxf(mx4[0], mx4[1]), fmaxf(mx4[2], mx4[3]));
;         mx = sel ? mx * SCL : -1e30f;
;         mx = quad_max(mx);
;         const float m_new = (mx > m_run[qs] + RESCALE_THR) ? mx : m_run[qs];
;         alpha[qs] = __builtin_amdgcn_exp2f(m_run[qs] - m_new);
;         m_run[qs] = m_new;
;         const float negm = sel ? -m_new : -1e30f;
;         float ps4[4];
; #pragma unroll
;         for (int mt = 0; mt < 4; ++mt) {
; #pragma unroll
;           for (int jj = 0; jj < 4; ++jj) s[qs][mt][jj] = __builtin_amdgcn_exp2f(fmaf(s[qs][mt][jj], SCL, negm));
;           ps4[mt] = (s[qs][mt][0] + s[qs][mt][1]) + (s[qs][mt][2] + s[qs][mt][3]);
;         }
;         l_run[qs] = l_run[qs] * alpha[qs] + ((ps4[0] + ps4[1]) + (ps4[2] + ps4[3]));
; #pragma unroll
;         for (int kk = 0; kk < 2; ++kk) {
;           uint4 pk;
;           pk.x = pack2(s[qs][2 * kk][0], s[qs][2 * kk][1]);
;           pk.y = pack2(s[qs][2 * kk][2], s[qs][2 * kk][3]);
;           pk.z = pack2(s[qs][2 * kk + 1][0], s[qs][2 * kk + 1][1]);
;           pk.w = pack2(s[qs][2 * kk + 1][2], s[qs][2 * kk + 1][3]);
;           pb[qs][kk] = *reinterpret_cast<bf16x8*>(&pk);
;         }
;       }
;       if (__ballot(alpha[0] != 1.0f || alpha[1] != 1.0f) != 0ull) {
; #pragma unroll
;         for (int qs = 0; qs < 2; ++qs)
; #pragma unroll
	v_max_f32_e32 v225, v207, v207
	v_cndmask_b32_e32 v220, v216, v230, vcc
	v_cmp_le_i32_e32 vcc, v200, v186
	v_max_f32_e32 v224, v225, v224
	v_max_f32_e32 v225, v219, v219
	v_cndmask_b32_e32 v221, v216, v231, vcc
	v_cmp_le_i32_e32 vcc, v201, v186
	v_max3_f32 v209, v203, v204, v209
	s_nop 0
	v_cndmask_b32_e32 v222, v216, v232, vcc
	v_cmp_le_i32_e32 vcc, v202, v186
	s_nop 1
	v_cndmask_b32_e32 v223, v216, v233, vcc
	v_cmp_le_i32_e32 vcc, v167, v198
	s_nop 1
	v_cndmask_b32_e32 v166, v216, v234, vcc
	v_cmp_lt_i32_e32 vcc, v167, v198
	s_nop 1
	v_cndmask_b32_e32 v167, v216, v235, vcc
	v_cmp_le_i32_e32 vcc, v174, v198
	s_nop 1
	v_cndmask_b32_e32 v174, v216, v236, vcc
	v_cmp_le_i32_e32 vcc, v175, v198
	s_nop 1
	v_cndmask_b32_e32 v175, v216, v237, vcc
	v_cmp_le_i32_e32 vcc, v176, v198
	s_nop 1
	v_cndmask_b32_e32 v176, v216, v238, vcc
	v_cmp_le_i32_e32 vcc, v177, v198
	s_nop 1
	v_cndmask_b32_e32 v177, v216, v239, vcc
	v_cmp_le_i32_e32 vcc, v178, v198
	s_nop 1
	v_cndmask_b32_e32 v178, v216, v240, vcc
	v_cmp_le_i32_e32 vcc, v179, v198
	s_nop 1
	v_cndmask_b32_e32 v179, v216, v241, vcc
	v_cmp_le_i32_e32 vcc, v183, v198
	s_nop 1
	v_cndmask_b32_e32 v183, v216, v242, vcc
	v_cmp_le_i32_e32 vcc, v191, v198
	s_nop 1
	v_cndmask_b32_e32 v191, v216, v243, vcc
	v_cmp_le_i32_e32 vcc, v196, v198
	s_nop 1
	v_cndmask_b32_e32 v196, v216, v244, vcc
	v_cmp_le_i32_e32 vcc, v197, v198
	s_nop 1
	v_cndmask_b32_e32 v197, v216, v245, vcc
	v_cmp_le_i32_e32 vcc, v199, v198
	s_nop 1
	v_cndmask_b32_e32 v199, v216, v226, vcc
	v_cmp_le_i32_e32 vcc, v200, v198
	v_max_f32_e32 v226, v218, v218
	v_max_f32_e32 v225, v226, v225
	v_cndmask_b32_e32 v200, v216, v227, vcc
	v_max_f32_e32 v226, v223, v223
	v_max_f32_e32 v227, v222, v222
	v_max_f32_e32 v226, v227, v226
	v_max3_f32 v226, v220, v221, v226
	v_max3_f32 v162, v224, v225, v226
	v_max3_f32 v162, v208, v209, v162
	v_mul_f32_e32 v162, 0x3e0293ee, v162
	v_cndmask_b32_e64 v162, v162, v214, s[10:11]
	v_mov_b32_e32 v163, v162
	s_nop 1
	v_permlane16_swap_b32_e32 v162, v163
	v_max_f32_e32 v163, v163, v163
	v_max_f32_e32 v162, v162, v162
	v_max_f32_e32 v162, v162, v163
	v_mov_b32_e32 v163, v162
	s_nop 1
	v_permlane32_swap_b32_e32 v162, v163
	v_cmp_le_i32_e32 vcc, v201, v198
	v_max_f32_e32 v163, v163, v163
	v_max_f32_e32 v162, v162, v162
	v_cndmask_b32_e32 v201, v216, v228, vcc
	v_cmp_le_i32_e32 vcc, v202, v198
	v_max_f32_e32 v162, v162, v163
	v_add_f32_e32 v163, 0x41000000, v164
	v_cndmask_b32_e32 v202, v216, v229, vcc
	v_cmp_gt_f32_e32 vcc, v162, v163
	v_max_f32_e32 v208, v174, v174
	v_max_f32_e32 v209, v178, v178
	v_cndmask_b32_e32 v162, v164, v162, vcc
	v_sub_f32_e32 v163, v164, v162
	v_exp_f32_e32 v164, v163
	v_max_f32_e32 v163, v175, v175
	v_max_f32_e32 v163, v208, v163
	v_max_f32_e32 v208, v179, v179
	v_max_f32_e32 v208, v209, v208
	v_max_f32_e32 v209, v191, v191
	v_max_f32_e32 v224, v183, v183
	v_max_f32_e32 v209, v224, v209
	v_max_f32_e32 v224, v197, v197
	v_max_f32_e32 v225, v196, v196
	v_max_f32_e32 v224, v225, v224
	v_max_f32_e32 v225, v202, v202
	v_max_f32_e32 v226, v201, v201
	v_max_f32_e32 v225, v226, v225
	v_max3_f32 v225, v199, v200, v225
	v_max3_f32 v163, v166, v167, v163
	v_max3_f32 v208, v176, v177, v208
	v_max3_f32 v160, v209, v224, v225
	v_max3_f32 v160, v163, v208, v160
	v_mul_f32_e32 v160, 0x3e0293ee, v160
	v_cndmask_b32_e64 v160, v160, v214, s[8:9]
	v_mov_b32_e32 v161, v160
	s_nop 1
	v_permlane16_swap_b32_e32 v160, v161
	v_max_f32_e32 v161, v161, v161
	v_max_f32_e32 v160, v160, v160
	v_max_f32_e32 v160, v160, v161
	v_mov_b32_e32 v161, v160
	s_nop 1
	v_permlane32_swap_b32_e32 v160, v161
	v_max_f32_e32 v161, v161, v161
	v_max_f32_e32 v160, v160, v160
	v_max_f32_e32 v160, v160, v161
	v_add_f32_e32 v161, 0x41000000, v165
	v_cmp_gt_f32_e32 vcc, v160, v161
	s_nop 1
	v_cndmask_b32_e32 v224, v165, v160, vcc
	v_sub_f32_e32 v160, v165, v224
	v_exp_f32_e32 v165, v160
	v_cmp_neq_f32_e32 vcc, 1.0, v164
	v_cmp_neq_f32_e64 s[12:13], 1.0, v165
	s_or_b64 vcc, vcc, s[12:13]
	s_cbranch_vccz .LBB0_333
	v_mov_b32_e32 v160, v165
	v_pk_mul_f32 v[156:157], v[156:157], v[164:165] op_sel_hi:[1,0]
	v_pk_mul_f32 v[158:159], v[158:159], v[164:165] op_sel_hi:[1,0]
	v_pk_mul_f32 v[148:149], v[148:149], v[164:165] op_sel_hi:[1,0]
	v_pk_mul_f32 v[150:151], v[150:151], v[164:165] op_sel_hi:[1,0]
	v_pk_mul_f32 v[144:145], v[144:145], v[164:165] op_sel_hi:[1,0]
	v_pk_mul_f32 v[146:147], v[146:147], v[164:165] op_sel_hi:[1,0]
	v_pk_mul_f32 v[140:141], v[140:141], v[164:165] op_sel_hi:[1,0]
	v_pk_mul_f32 v[142:143], v[142:143], v[164:165] op_sel_hi:[1,0]
	v_pk_mul_f32 v[136:137], v[136:137], v[164:165] op_sel_hi:[1,0]
	v_pk_mul_f32 v[138:139], v[138:139], v[164:165] op_sel_hi:[1,0]
	v_pk_mul_f32 v[128:129], v[128:129], v[164:165] op_sel_hi:[1,0]
	v_pk_mul_f32 v[130:131], v[130:131], v[164:165] op_sel_hi:[1,0]
	v_pk_mul_f32 v[120:121], v[120:121], v[164:165] op_sel_hi:[1,0]
	v_pk_mul_f32 v[122:123], v[122:123], v[164:165] op_sel_hi:[1,0]
	v_pk_mul_f32 v[112:113], v[112:113], v[164:165] op_sel_hi:[1,0]
	v_pk_mul_f32 v[114:115], v[114:115], v[164:165] op_sel_hi:[1,0]
	v_pk_mul_f32 v[154:155], v[154:155], v[160:161] op_sel_hi:[1,0]
	v_pk_mul_f32 v[152:153], v[152:153], v[160:161] op_sel_hi:[1,0]
	v_pk_mul_f32 v[134:135], v[134:135], v[160:161] op_sel_hi:[1,0]
	v_pk_mul_f32 v[132:133], v[132:133], v[160:161] op_sel_hi:[1,0]
	v_pk_mul_f32 v[126:127], v[126:127], v[160:161] op_sel_hi:[1,0]
	v_pk_mul_f32 v[124:125], v[124:125], v[160:161] op_sel_hi:[1,0]
	v_pk_mul_f32 v[118:119], v[118:119], v[160:161] op_sel_hi:[1,0]
	v_pk_mul_f32 v[116:117], v[116:117], v[160:161] op_sel_hi:[1,0]
	v_pk_mul_f32 v[110:111], v[110:111], v[160:161] op_sel_hi:[1,0]
	v_pk_mul_f32 v[108:109], v[108:109], v[160:161] op_sel_hi:[1,0]
	v_pk_mul_f32 v[106:107], v[106:107], v[160:161] op_sel_hi:[1,0]
	v_pk_mul_f32 v[104:105], v[104:105], v[160:161] op_sel_hi:[1,0]
	v_pk_mul_f32 v[102:103], v[102:103], v[160:161] op_sel_hi:[1,0]
	v_pk_mul_f32 v[100:101], v[100:101], v[160:161] op_sel_hi:[1,0]
	v_pk_mul_f32 v[98:99], v[98:99], v[160:161] op_sel_hi:[1,0]
	v_pk_mul_f32 v[96:97], v[96:97], v[160:161] op_sel_hi:[1,0]

; __device__ __forceinline__ float bf2f(unsigned short h) { return __uint_as_float(((unsigned)h) << 16); }
; __device__ __forceinline__ float bflo(unsigned u) { return __uint_as_float(u << 16); }
; __device__ __forceinline__ float bfhi(unsigned u) { return __uint_as_float(u & 0xffff0000u); }
; __device__ __forceinline__ float sigmoid_f(float z) { return 1.0f / (1.0f + __expf(-z)); }
; template <int MODE> ...
;     ...
; #pragma unroll
;   for (int qs = 0; qs < 2; ++qs) {
;     float l = l_run[qs];
;     l = quad_sum(l);
;     l_out[qs] = l;
;   }
; __device__ __forceinline__ void attn_phase(const bf16_t* __restrict__ proj, const bf16_t* __restrict__ KC,
;                            const bf16_t* __restrict__ VCT, const bf16_t* __restrict__ VT,
;                            bf16_t* __restrict__ mixed) {
;     ...
;       for (int qs = 0; qs < 2; ++qs) {
;         const float g1 = sigmoid_f(bf2f(proj[(row0 + qs * 4) * NPAD + OFF_G + head * 3 + 1])) / l[qs];
; #pragma unroll
;         for (int dt = 0; dt < 8; ++dt) {
;           uint2 pv = oacc[((w * 2 + qs) * 8 + dt) * 64 + lane];
;           uint2 ov;
;           ov.x = pack2(bflo(pv.x) + g1 * o[qs][dt][0], bfhi(pv.x) + g1 * o[qs][dt][1]);
;           ov.y = pack2(bflo(pv.y) + g1 * o[qs][dt][2], bfhi(pv.y) + g1 * o[qs][dt][3]);
;           oacc[((w * 2 + qs) * 8 + dt) * 64 + lane] = ov;
;         }
;       }
.LBB0_335:
	v_mad_u64_u32 v[32:33], s[8:9], v184, s81, 0
	v_mov_b32_e32 v191, v181
	v_mad_i32_i24 v33, v185, s81, v33
	v_lshl_add_u64 v[34:35], s[36:37], 0, v[190:191]
	v_lshl_add_u64 v[48:49], v[34:35], 0, v[32:33]
	v_add_co_u32_e32 v32, vcc, s84, v48
	s_nop 1
	v_addc_co_u32_e32 v33, vcc, 0, v49, vcc
	s_barrier
	global_load_ushort v50, v[32:33], off offset:2050
	v_mov_b32_e32 v52, v197
	v_add_co_u32_e32 v48, vcc, s92, v48
	s_nop 0
	v_permlane16_swap_b32_e32 v197, v52
	v_addc_co_u32_e32 v49, vcc, 0, v49, vcc
	ds_read2st64_b64 v[32:35], v187 offset1:1
	ds_read2st64_b64 v[36:39], v187 offset0:2 offset1:3
	ds_read2st64_b64 v[40:43], v187 offset0:4 offset1:5
	ds_read2st64_b64 v[44:47], v187 offset0:6 offset1:7
	v_add_f32_e32 v53, v197, v52
	global_load_ushort v52, v[48:49], off offset:2
	v_mov_b32_e32 v51, v196
	s_nop 1
	v_permlane16_swap_b32_e32 v196, v51
	v_add_f32_e32 v51, v196, v51
	v_mov_b32_e32 v183, v51
	s_nop 1
	v_permlane32_swap_b32_e32 v51, v183
	s_waitcnt lgkmcnt(3)
	v_lshlrev_b32_e32 v48, 16, v32
	v_and_b32_e32 v49, 0xffff0000, v32
	v_lshlrev_b32_e32 v32, 16, v33
	v_and_b32_e32 v33, 0xffff0000, v33
	v_lshlrev_b32_e32 v54, 16, v34
	v_and_b32_e32 v55, 0xffff0000, v34
	v_lshlrev_b32_e32 v34, 16, v35
	v_and_b32_e32 v35, 0xffff0000, v35
	s_waitcnt lgkmcnt(2)
	v_lshlrev_b32_e32 v56, 16, v36
	v_and_b32_e32 v57, 0xffff0000, v36
	v_lshlrev_b32_e32 v36, 16, v37
	v_and_b32_e32 v37, 0xffff0000, v37
	v_lshlrev_b32_e32 v58, 16, v38
	v_and_b32_e32 v59, 0xffff0000, v38
	v_lshlrev_b32_e32 v38, 16, v39
	v_and_b32_e32 v39, 0xffff0000, v39
	s_waitcnt lgkmcnt(1)
	v_lshlrev_b32_e32 v60, 16, v40
	v_and_b32_e32 v61, 0xffff0000, v40
	v_lshlrev_b32_e32 v40, 16, v41
	v_and_b32_e32 v41, 0xffff0000, v41
	v_lshlrev_b32_e32 v62, 16, v42
	v_and_b32_e32 v63, 0xffff0000, v42
	v_lshlrev_b32_e32 v42, 16, v43
	v_and_b32_e32 v43, 0xffff0000, v43
	v_mov_b32_e32 v64, v53
	s_nop 1
	v_permlane32_swap_b32_e32 v53, v64
	s_mov_b32 s12, 0
	v_add_u32_e32 v169, 0xfffffe00, v186
	v_add_u32_e32 v170, 0xfffffe04, v186
	s_mov_b32 s16, 0
	s_waitcnt vmcnt(1)
	v_lshlrev_b32_e32 v50, 16, v50
	v_mul_f32_e32 v50, 0xbfb8aa3b, v50
	v_exp_f32_e32 v50, v50
	s_nop 0
	v_pk_add_f32 v[50:51], v[50:51], v[182:183]
	s_nop 0
	v_div_scale_f32 v65, s[8:9], v50, v50, 1.0
	v_rcp_f32_e32 v66, v65
	v_div_scale_f32 v67, vcc, 1.0, v50, 1.0
	v_mov_b32_e32 v183, v64
	v_fma_f32 v68, -v65, v66, 1.0
	v_fmac_f32_e32 v66, v68, v66
	v_mul_f32_e32 v68, v67, v66
	v_fma_f32 v69, -v65, v68, v67
	v_fmac_f32_e32 v68, v69, v66
	v_fma_f32 v65, -v65, v68, v67
	v_div_fmas_f32 v65, v65, v66, v68
	v_div_fixup_f32 v50, v65, v50, 1.0
	v_div_scale_f32 v65, s[8:9], v51, v51, v50
	v_rcp_f32_e32 v66, v65
	v_div_scale_f32 v67, vcc, v50, v51, v50
	v_fma_f32 v68, -v65, v66, 1.0
	v_fmac_f32_e32 v66, v68, v66
	v_mul_f32_e32 v68, v67, v66
	v_fma_f32 v69, -v65, v68, v67
	v_fmac_f32_e32 v68, v69, v66
	v_fma_f32 v65, -v65, v68, v67
	v_div_fmas_f32 v65, v65, v66, v68
	v_div_fixup_f32 v50, v65, v51, v50
	v_pk_fma_f32 v[48:49], v[124:125], v[50:51], v[48:49] op_sel_hi:[1,0,1]
	v_pk_fma_f32 v[32:33], v[126:127], v[50:51], v[32:33] op_sel_hi:[1,0,1]
	v_pk_fma_f32 v[54:55], v[128:129], v[50:51], v[54:55] op_sel_hi:[1,0,1]
	v_pk_fma_f32 v[34:35], v[130:131], v[50:51], v[34:35] op_sel_hi:[1,0,1]
	v_pk_fma_f32 v[56:57], v[132:133], v[50:51], v[56:57] op_sel_hi:[1,0,1]
	v_pk_fma_f32 v[36:37], v[134:135], v[50:51], v[36:37] op_sel_hi:[1,0,1]
	v_pk_fma_f32 v[58:59], v[136:137], v[50:51], v[58:59] op_sel_hi:[1,0,1]
	v_pk_fma_f32 v[38:39], v[138:139], v[50:51], v[38:39] op_sel_hi:[1,0,1]
	v_pk_fma_f32 v[60:61], v[144:145], v[50:51], v[60:61] op_sel_hi:[1,0,1]
	v_pk_fma_f32 v[40:41], v[146:147], v[50:51], v[40:41] op_sel_hi:[1,0,1]
	v_pk_fma_f32 v[62:63], v[148:149], v[50:51], v[62:63] op_sel_hi:[1,0,1]
	v_pk_fma_f32 v[42:43], v[150:151], v[50:51], v[42:43] op_sel_hi:[1,0,1]
	v_cvt_pk_bf16_f32 v48, v48, v49
	v_cvt_pk_bf16_f32 v49, v32, v33
	v_cvt_pk_bf16_f32 v32, v54, v55
	v_cvt_pk_bf16_f32 v33, v34, v35
	v_cvt_pk_bf16_f32 v34, v56, v57
	v_cvt_pk_bf16_f32 v35, v36, v37
	v_cvt_pk_bf16_f32 v36, v58, v59
	v_cvt_pk_bf16_f32 v37, v38, v39
	v_cvt_pk_bf16_f32 v38, v60, v61
	v_cvt_pk_bf16_f32 v39, v40, v41
	v_cvt_pk_bf16_f32 v40, v62, v63
	v_cvt_pk_bf16_f32 v41, v42, v43
	ds_write2st64_b64 v187, v[48:49], v[32:33] offset1:1
	ds_write2st64_b64 v187, v[34:35], v[36:37] offset0:2 offset1:3
	ds_write2st64_b64 v187, v[38:39], v[40:41] offset0:4 offset1:5
	s_waitcnt lgkmcnt(3)
	v_lshlrev_b32_e32 v32, 16, v44
	v_and_b32_e32 v33, 0xffff0000, v44
	v_lshlrev_b32_e32 v34, 16, v45
	v_and_b32_e32 v35, 0xffff0000, v45
	v_pk_fma_f32 v[32:33], v[152:153], v[50:51], v[32:33] op_sel_hi:[1,0,1]
	v_pk_fma_f32 v[34:35], v[154:155], v[50:51], v[34:35] op_sel_hi:[1,0,1]
	v_cvt_pk_bf16_f32 v32, v32, v33
	v_cvt_pk_bf16_f32 v33, v34, v35
	s_waitcnt vmcnt(0)
	v_lshlrev_b32_e32 v35, 16, v52
	v_mul_f32_e32 v35, 0xbfb8aa3b, v35
	v_exp_f32_e32 v52, v35
	v_lshlrev_b32_e32 v34, 16, v46
	v_and_b32_e32 v35, 0xffff0000, v46
	v_pk_fma_f32 v[34:35], v[156:157], v[50:51], v[34:35] op_sel_hi:[1,0,1]
	v_pk_add_f32 v[36:37], v[52:53], v[182:183]
	v_cvt_pk_bf16_f32 v34, v34, v35
	v_div_scale_f32 v40, s[8:9], v36, v36, 1.0
	v_rcp_f32_e32 v41, v40
	v_lshlrev_b32_e32 v38, 16, v47
	v_and_b32_e32 v39, 0xffff0000, v47
	v_pk_fma_f32 v[38:39], v[158:159], v[50:51], v[38:39] op_sel_hi:[1,0,1]
	v_fma_f32 v35, -v40, v41, 1.0
	v_fmac_f32_e32 v41, v35, v41
	v_div_scale_f32 v35, vcc, 1.0, v36, 1.0
	v_mul_f32_e32 v42, v35, v41
	v_fma_f32 v43, -v40, v42, v35
	v_fmac_f32_e32 v42, v43, v41
	v_fma_f32 v35, -v40, v42, v35
	v_div_fmas_f32 v35, v35, v41, v42
	v_div_fixup_f32 v36, v35, v36, 1.0
	v_div_scale_f32 v40, s[8:9], v37, v37, v36
	v_rcp_f32_e32 v41, v40
	v_cvt_pk_bf16_f32 v35, v38, v39
	ds_write2st64_b64 v187, v[32:33], v[34:35] offset0:6 offset1:7
	s_lshl_b32 s8, s10, 1
	v_fma_f32 v32, -v40, v41, 1.0
	v_fmac_f32_e32 v41, v32, v41
	v_div_scale_f32 v32, vcc, v36, v37, v36
	v_mul_f32_e32 v38, v32, v41
	v_fma_f32 v33, -v40, v38, v32
	v_fmac_f32_e32 v38, v33, v41
	v_fma_f32 v39, -v40, v38, v32
	ds_read2st64_b64 v[32:35], v187 offset0:8 offset1:9
	v_div_fmas_f32 v38, v39, v41, v38
	v_div_fixup_f32 v40, v38, v37, v36
	ds_read2st64_b64 v[36:39], v187 offset0:10 offset1:11
	s_add_u32 s8, s25, s8
	s_waitcnt lgkmcnt(1)
; __device__ __forceinline__ float bflo(unsigned u) { return __uint_as_float(u << 16); }
; __device__ __forceinline__ float bfhi(unsigned u) { return __uint_as_float(u & 0xffff0000u); }
; template <int MODE> ...
;     ...
;   const int krow0 = tid >> 4, kch = tid & 15;
;   const int vrow0 = tid >> 3, vch = tid & 7;
;   const bf16_t* kp = Kg + (size_t)(jlo * 64 + krow0) * NPAD + kch * 8;
;   const bf16_t* vp0 = VTg + (size_t)vrow0 * SEQ + jlo * 64 + vch * 8;
;   uint4 kr0 = *(const uint4*)kp, kr1 = *(const uint4*)(kp + (size_t)32 * NPAD);
;   uint4 vr0 = *(const uint4*)vp0, vr1 = *(const uint4*)(vp0 + (size_t)64 * SEQ);
;   __syncthreads();
;   stage_write_k((bf16_t*)smem, krow0, kch, kr0, kr1);
;   stage_write_v((bf16_t*)(smem + KT_BYTES), vrow0, vch, vr0, vr1);
; __device__ __forceinline__ void attn_phase(const bf16_t* __restrict__ proj, const bf16_t* __restrict__ KC,
;                            const bf16_t* __restrict__ VCT, const bf16_t* __restrict__ VT,
;                            bf16_t* __restrict__ mixed) {
;     ...
; #pragma unroll
;         for (int dt = 0; dt < 8; ++dt) {
;           uint2 pv = oacc[((w * 2 + qs) * 8 + dt) * 64 + lane];
;           uint2 ov;
;           ov.x = pack2(bflo(pv.x) + g1 * o[qs][dt][0], bfhi(pv.x) + g1 * o[qs][dt][1]);
;           ov.y = pack2(bflo(pv.y) + g1 * o[qs][dt][2], bfhi(pv.y) + g1 * o[qs][dt][3]);
;           oacc[((w * 2 + qs) * 8 + dt) * 64 + lane] = ov;
;         }
;       }
	v_lshlrev_b32_e32 v42, 16, v32
	v_and_b32_e32 v43, 0xffff0000, v32
	v_pk_fma_f32 v[42:43], v[96:97], v[40:41], v[42:43] op_sel_hi:[1,0,1]
	s_addc_u32 s9, s60, 0
	v_cvt_pk_bf16_f32 v32, v42, v43
	v_lshlrev_b32_e32 v42, 16, v33
	v_and_b32_e32 v43, 0xffff0000, v33
	v_pk_fma_f32 v[42:43], v[98:99], v[40:41], v[42:43] op_sel_hi:[1,0,1]
	s_add_u32 s8, s8, 0x6000
	v_cvt_pk_bf16_f32 v33, v42, v43
	v_lshlrev_b32_e32 v42, 16, v34
	v_and_b32_e32 v43, 0xffff0000, v34
	v_pk_fma_f32 v[42:43], v[100:101], v[40:41], v[42:43] op_sel_hi:[1,0,1]
	s_addc_u32 s9, s9, 0
	v_cvt_pk_bf16_f32 v34, v42, v43
	v_lshlrev_b32_e32 v42, 16, v35
	v_and_b32_e32 v43, 0xffff0000, v35
	v_pk_fma_f32 v[42:43], v[102:103], v[40:41], v[42:43] op_sel_hi:[1,0,1]
	v_mov_b32_e32 v144, 0
	v_cvt_pk_bf16_f32 v35, v42, v43
	ds_write2st64_b64 v187, v[32:33], v[34:35] offset0:8 offset1:9
	s_waitcnt lgkmcnt(1)
	v_lshlrev_b32_e32 v32, 16, v36
	v_and_b32_e32 v33, 0xffff0000, v36
	v_pk_fma_f32 v[32:33], v[108:109], v[40:41], v[32:33] op_sel_hi:[1,0,1]
	v_lshlrev_b32_e32 v42, 16, v39
	v_cvt_pk_bf16_f32 v36, v32, v33
	v_lshlrev_b32_e32 v32, 16, v37
	v_and_b32_e32 v33, 0xffff0000, v37
	v_pk_fma_f32 v[32:33], v[110:111], v[40:41], v[32:33] op_sel_hi:[1,0,1]
	v_and_b32_e32 v43, 0xffff0000, v39
	v_cvt_pk_bf16_f32 v37, v32, v33
	v_lshlrev_b32_e32 v32, 16, v38
	v_and_b32_e32 v33, 0xffff0000, v38
	v_pk_fma_f32 v[32:33], v[112:113], v[40:41], v[32:33] op_sel_hi:[1,0,1]
	v_pk_fma_f32 v[42:43], v[114:115], v[40:41], v[42:43] op_sel_hi:[1,0,1]
	v_cvt_pk_bf16_f32 v38, v32, v33
	ds_read2st64_b64 v[32:35], v187 offset0:12 offset1:13
	v_cvt_pk_bf16_f32 v39, v42, v43
	ds_write2st64_b64 v187, v[36:37], v[38:39] offset0:10 offset1:11
	ds_read2st64_b64 v[36:39], v187 offset0:14 offset1:15
	v_mov_b32_e32 v150, 0xf149f2ca
	s_waitcnt lgkmcnt(2)
	v_lshlrev_b32_e32 v42, 16, v32
	v_and_b32_e32 v43, 0xffff0000, v32
	v_pk_fma_f32 v[42:43], v[104:105], v[40:41], v[42:43] op_sel_hi:[1,0,1]
	v_mov_b32_e32 v151, v150
	v_cvt_pk_bf16_f32 v32, v42, v43
	v_lshlrev_b32_e32 v42, 16, v33
	v_and_b32_e32 v43, 0xffff0000, v33
	v_pk_fma_f32 v[42:43], v[106:107], v[40:41], v[42:43] op_sel_hi:[1,0,1]
	v_mov_b32_e32 v145, v144
	v_cvt_pk_bf16_f32 v33, v42, v43
	v_lshlrev_b32_e32 v42, 16, v34
	v_and_b32_e32 v43, 0xffff0000, v34
	v_pk_fma_f32 v[42:43], v[116:117], v[40:41], v[42:43] op_sel_hi:[1,0,1]
	s_nop 0
	v_cvt_pk_bf16_f32 v34, v42, v43
	v_lshlrev_b32_e32 v42, 16, v35
	v_and_b32_e32 v43, 0xffff0000, v35
	v_pk_fma_f32 v[42:43], v[118:119], v[40:41], v[42:43] op_sel_hi:[1,0,1]
	s_nop 0
	v_cvt_pk_bf16_f32 v35, v42, v43
	ds_write2st64_b64 v187, v[32:33], v[34:35] offset0:12 offset1:13
	s_waitcnt lgkmcnt(1)
	v_lshlrev_b32_e32 v32, 16, v36
	v_and_b32_e32 v33, 0xffff0000, v36
	v_lshlrev_b32_e32 v34, 16, v37
	v_and_b32_e32 v35, 0xffff0000, v37
	v_pk_fma_f32 v[32:33], v[120:121], v[40:41], v[32:33] op_sel_hi:[1,0,1]
	v_pk_fma_f32 v[34:35], v[122:123], v[40:41], v[34:35] op_sel_hi:[1,0,1]
	v_cvt_pk_bf16_f32 v32, v32, v33
	v_cvt_pk_bf16_f32 v33, v34, v35
	v_lshlrev_b32_e32 v34, 16, v38
	v_and_b32_e32 v35, 0xffff0000, v38
	v_lshlrev_b32_e32 v36, 16, v39
	v_and_b32_e32 v37, 0xffff0000, v39
	v_pk_fma_f32 v[34:35], v[140:141], v[40:41], v[34:35] op_sel_hi:[1,0,1]
	v_pk_fma_f32 v[36:37], v[142:143], v[40:41], v[36:37] op_sel_hi:[1,0,1]
	v_cvt_pk_bf16_f32 v34, v34, v35
	v_cvt_pk_bf16_f32 v35, v36, v37
	v_mov_b32_e32 v43, v254
	ds_write2st64_b64 v187, v[32:33], v[34:35] offset0:14 offset1:15
	v_sub_u32_e64 v42, s96, 8 clamp
	v_mov_b64_e32 v[34:35], s[8:9]
	v_ashrrev_i32_e32 v45, 4, v43
	v_and_b32_e32 v44, 15, v43
	v_ashrrev_i32_e32 v32, 3, v43
	v_lshl_add_u32 v33, v42, 6, v45
	v_mad_i64_i32 v[34:35], s[8:9], v33, s81, v[34:35]
	v_lshlrev_b32_e32 v36, 4, v44
	v_mov_b32_e32 v37, v181
	v_ashrrev_i32_e32 v33, 31, v32
	v_lshl_add_u64 v[146:147], v[34:35], 0, v[36:37]
	v_lshlrev_b64 v[34:35], 13, v[32:33]
	v_and_b32_e32 v46, 7, v43
	v_lshl_add_u64 v[34:35], s[14:15], 0, v[34:35]
	v_lshlrev_b32_e32 v38, 7, v42
	v_mov_b32_e32 v39, v181
	v_add_co_u32_e32 v40, vcc, s89, v146
	global_load_dwordx4 v[96:99], v[146:147], off
	s_nop 0
	v_addc_co_u32_e32 v41, vcc, 0, v147, vcc
	v_lshl_add_u64 v[34:35], v[34:35], 0, v[38:39]
	v_lshlrev_b32_e32 v38, 4, v46
	global_load_dwordx4 v[100:103], v[40:41], off
	v_lshl_add_u64 v[34:35], v[34:35], 0, v[38:39]
	v_add_co_u32_e32 v38, vcc, s93, v34
	v_lshl_add_u64 v[148:149], v[34:35], 0, s[52:53]
	s_nop 0
	v_addc_co_u32_e32 v39, vcc, 0, v35, vcc
	global_load_dwordx4 v[104:107], v[38:39], off
	v_add_co_u32_e32 v38, vcc, s94, v34
	v_mul_lo_u32 v34, v45, s86
	s_nop 0
	v_addc_co_u32_e32 v39, vcc, 0, v35, vcc
	global_load_dwordx4 v[108:111], v[38:39], off
	v_lshlrev_b32_e32 v164, 1, v34
	v_add3_u32 v34, 16, v164, v36
	v_lshrrev_b32_e32 v167, 6, v254
	v_lshrrev_b32_e32 v168, 7, v254
	v_xor_b32_e32 v167, v167, v168
	v_and_b32_e32 v167, 1, v167
	v_bfe_u32 v168, v254, 0, 1
	v_and_b32_e32 v168, v168, v167
	v_lshlrev_b32_e32 v167, 4, v167
	v_lshlrev_b32_e32 v168, 5, v168
	v_sub_u32_e32 v167, v167, v168
	v_add_u32_e32 v34, v34, v167
	v_lshlrev_b32_e32 v33, 3, v43
	s_waitcnt lgkmcnt(0)
	s_barrier
; __device__ __forceinline__ void stage_write_v(bf16_t* Vt, int vrow0, int vch, uint4 vr0, uint4 vr1) {
;   const int g4a = 2 * vch, g4b = 2 * vch + 1;
;   const int pa = (g4a >> 3) * 32 + (g4a & 3) * 8 + ((g4a >> 2) & 1) * 4;
;   const int pb = (g4b >> 3) * 32 + (g4b & 3) * 8 + ((g4b >> 2) & 1) * 4;
;   *(uint2*)(Vt + vrow0 * VT_STRIDE + pa) = make_uint2(vr0.x, vr0.y);
;   *(uint2*)(Vt + vrow0 * VT_STRIDE + pb) = make_uint2(vr0.z, vr0.w);
;   *(uint2*)(Vt + (vrow0 + 64) * VT_STRIDE + pa) = make_uint2(vr1.x, vr1.y);
;   *(uint2*)(Vt + (vrow0 + 64) * VT_STRIDE + pb) = make_uint2(vr1.z, vr1.w);
; }
; template <int MODE> ...
;   int tid = threadIdx.x;
;   asm volatile("" : "+v"(tid));
;   const int lane = tid & 63, c = lane & 15, quad = lane >> 4;
;   float m_run[2] = {-1e30f, -1e30f}, l_run[2] = {0.f, 0.f};
; #pragma unroll
;   for (int qs = 0; qs < 2; ++qs)
; #pragma unroll
;     for (int i = 0; i < 8; ++i) o[qs][i] = (f32x4){0.f, 0.f, 0.f, 0.f};
;   const int krow0 = tid >> 4, kch = tid & 15;
;   const int vrow0 = tid >> 3, vch = tid & 7;
;   const bf16_t* kp = Kg + (size_t)(jlo * 64 + krow0) * NPAD + kch * 8;
;   const bf16_t* vp0 = VTg + (size_t)vrow0 * SEQ + jlo * 64 + vch * 8;
;   uint4 kr0 = *(const uint4*)kp, kr1 = *(const uint4*)(kp + (size_t)32 * NPAD);
;   uint4 vr0 = *(const uint4*)vp0, vr1 = *(const uint4*)(vp0 + (size_t)64 * SEQ);
;   __syncthreads();
;   stage_write_k((bf16_t*)smem, krow0, kch, kr0, kr1);
;   stage_write_v((bf16_t*)(smem + KT_BYTES), vrow0, vch, vr0, vr1);
;   __syncthreads();
	s_waitcnt vmcnt(3)
	ds_write_b128 v34, v[96:99]
	s_waitcnt vmcnt(2)
	ds_write_b128 v34, v[100:103] offset:8704
	v_lshlrev_b32_e32 v34, 4, v43
	v_lshlrev_b32_e32 v35, 1, v43
	v_and_b32_e32 v33, 32, v33
	v_and_b32_e32 v34, 16, v34
	v_and_b32_e32 v35, 4, v35
	v_or3_b32 v33, v33, v34, v35
	v_mul_lo_u32 v32, v32, s87
	v_lshlrev_b32_e32 v165, 1, v32
	v_lshlrev_b32_e32 v166, 1, v33
	v_lshrrev_b32_e32 v167, 5, v254
	v_lshrrev_b32_e32 v168, 6, v254
	v_xor_b32_e32 v167, v167, v168
	v_and_b32_e32 v167, 1, v167
	v_lshlrev_b32_e32 v167, 4, v167
	v_add_u32_e32 v166, v166, v167
	v_add3_u32 v32, 16, v165, v166
	v_xor_b32_e32 v167, 16, v166
	v_add3_u32 v168, 16, v165, v167
	v_add_u32_e32 v33, 0x4000, v32
	v_add_u32_e32 v32, 0x6800, v32
	s_min_u32 s8, s96, 8
	s_waitcnt vmcnt(0)
	ds_write_b64 v32, v[108:109]
	ds_write_b64 v168, v[110:111] offset:26624
	v_bfe_u32 v32, v43, 4, 2
	v_lshlrev_b32_e32 v37, 3, v44
	v_lshl_add_u32 v171, v32, 4, 16
	v_lshrrev_b32_e32 v172, 2, v254
	v_lshrrev_b32_e32 v173, 3, v254
	v_xor_b32_e32 v172, v172, v173
	v_and_b32_e32 v172, 1, v172
	v_bfe_u32 v173, v254, 4, 1
	v_and_b32_e32 v173, v173, v172
	v_lshlrev_b32_e32 v172, 4, v172
	v_lshlrev_b32_e32 v173, 5, v173
	v_sub_u32_e32 v172, v172, v173
	v_add_u32_e32 v171, v171, v172
	v_lshl_add_u32 v32, v32, 2, s97
	s_lshl_b32 s14, s8, 6
	v_mov_b32_e32 v34, v181
	v_mov_b32_e32 v35, v181
	v_readfirstlane_b32 s13, v42
	ds_write_b64 v33, v[104:105] offset:1024
	ds_write_b64 v168, v[106:107] offset:17408
	v_mul_u32_u24_e32 v167, 0x110, v44
	v_mul_u32_u24_e32 v168, 0x90, v44
	v_subrev_u32_e32 v172, s14, v32
	v_mov_b32_e32 v32, v181
	v_mov_b32_e32 v33, v181
	v_lshlrev_b32_e32 v173, 1, v37
	v_lshrrev_b32_e32 v36, 6, v254
	v_lshrrev_b32_e32 v37, 7, v254
	v_xor_b32_e32 v36, v36, v37
	v_and_b32_e32 v36, 1, v36
	v_bfe_u32 v37, v254, 0, 1
	v_and_b32_e32 v37, v37, v36
	v_lshlrev_b32_e32 v36, 4, v36
	v_lshlrev_b32_e32 v37, 5, v37
	v_sub_u32_e32 v36, v36, v37
	v_add_u32_e32 v173, v173, v36
	v_mov_b64_e32 v[38:39], v[34:35]
	v_mov_b64_e32 v[42:43], v[34:35]
	v_mov_b64_e32 v[46:47], v[34:35]
	v_mov_b64_e32 v[50:51], v[34:35]
	v_mov_b64_e32 v[54:55], v[34:35]
	v_mov_b64_e32 v[58:59], v[34:35]
	v_mov_b64_e32 v[62:63], v[34:35]
	v_mov_b64_e32 v[66:67], v[34:35]
	v_mov_b64_e32 v[70:71], v[34:35]
	v_mov_b64_e32 v[74:75], v[34:35]
	v_mov_b64_e32 v[78:79], v[34:35]
	v_mov_b64_e32 v[82:83], v[34:35]
	v_mov_b64_e32 v[86:87], v[34:35]
	v_mov_b64_e32 v[90:91], v[34:35]
	v_mov_b64_e32 v[94:95], v[34:35]
	s_add_i32 s15, s14, 0xfffffe00
	v_mov_b64_e32 v[36:37], v[32:33]
	v_mov_b64_e32 v[40:41], v[32:33]
	v_mov_b64_e32 v[44:45], v[32:33]
	v_mov_b64_e32 v[48:49], v[32:33]
	v_mov_b64_e32 v[52:53], v[32:33]
	v_mov_b64_e32 v[56:57], v[32:33]
	v_mov_b64_e32 v[60:61], v[32:33]
	v_mov_b64_e32 v[64:65], v[32:33]
	v_mov_b64_e32 v[68:69], v[32:33]
	v_mov_b64_e32 v[72:73], v[32:33]
	v_mov_b64_e32 v[76:77], v[32:33]
	v_mov_b64_e32 v[80:81], v[32:33]
	v_mov_b64_e32 v[84:85], v[32:33]
	v_mov_b64_e32 v[88:89], v[32:33]
	v_mov_b64_e32 v[92:93], v[32:33]
	s_waitcnt lgkmcnt(0)
	s_barrier
	s_branch .LBB0_337

; template <int MODE> ...
;     ...
;         const float negm = sel ? -m_new : -1e30f;
;         float ps4[4];
; #pragma unroll
;         for (int mt = 0; mt < 4; ++mt) {
; #pragma unroll
;           for (int jj = 0; jj < 4; ++jj) s[qs][mt][jj] = __builtin_amdgcn_exp2f(fmaf(s[qs][mt][jj], SCL, negm));
;           ps4[mt] = (s[qs][mt][0] + s[qs][mt][1]) + (s[qs][mt][2] + s[qs][mt][3]);
;         }
;         l_run[qs] = l_run[qs] * alpha[qs] + ((ps4[0] + ps4[1]) + (ps4[2] + ps4[3]));
; #pragma unroll
;         for (int kk = 0; kk < 2; ++kk) {
;           uint4 pk;
;           pk.x = pack2(s[qs][2 * kk][0], s[qs][2 * kk][1]);
;           pk.y = pack2(s[qs][2 * kk][2], s[qs][2 * kk][3]);
;           pk.z = pack2(s[qs][2 * kk + 1][0], s[qs][2 * kk + 1][1]);
;           pk.w = pack2(s[qs][2 * kk + 1][2], s[qs][2 * kk + 1][3]);
;           pb[qs][kk] = *reinterpret_cast<bf16x8*>(&pk);
;         }
;       }
;       if (__ballot(alpha[0] != 1.0f || alpha[1] != 1.0f) != 0ull) {
; #pragma unroll
;         for (int qs = 0; qs < 2; ++qs)
; #pragma unroll
;           for (int dt = 0; dt < 8; ++dt) {
;             o[qs][dt][0] *= alpha[qs]; o[qs][dt][1] *= alpha[qs]; o[qs][dt][2] *= alpha[qs]; o[qs][dt][3] *= alpha[qs];
;           }
;       }
; #pragma unroll
;       for (int kk = 0; kk < 2; ++kk)
; #pragma unroll
;         for (int dt = 0; dt < 8; ++dt) {
;           bf16x8 a = *(const bf16x8*)(Vt + (dt * 16 + c) * VT_STRIDE + kk * 32 + quad * 8);
;           o[0][dt] = __builtin_amdgcn_mfma_f32_16x16x32_bf16(a, pb[0][kk], o[0][dt], 0, 0, 0);
;           o[1][dt] = __builtin_amdgcn_mfma_f32_16x16x32_bf16(a, pb[1][kk], o[1][dt], 0, 0, 0);
;         }
;     }
;     if (j < jhi) {
;       stage_write_k((bf16_t*)(smem + (cb ^ 1) * STAGE_BYTES), krow0, kch, kr0, kr1);
;       stage_write_v((bf16_t*)(smem + (cb ^ 1) * STAGE_BYTES + KT_BYTES), vrow0, vch, vr0, vr1);
;     }
;     __syncthreads();
.LBB0_343:
	v_fma_f32 v140, v140, s42, -v150
	v_exp_f32_e32 v154, v140
	v_fma_f32 v140, v141, s42, -v150
	v_exp_f32_e32 v162, v140
	v_fma_f32 v140, v142, s42, -v150
	v_exp_f32_e32 v142, v140
	v_fma_f32 v140, v143, s42, -v150
	v_fma_f32 v136, v136, s42, -v150
	v_exp_f32_e32 v160, v140
	v_exp_f32_e32 v140, v136
	v_fma_f32 v136, v137, s42, -v150
	v_fma_f32 v117, v117, s42, -v150
	v_exp_f32_e32 v158, v136
	v_fma_f32 v136, v138, s42, -v150
	v_exp_f32_e32 v138, v117
	v_fma_f32 v117, v118, s42, -v150
	v_fma_f32 v118, v132, s42, -v151
	v_exp_f32_e32 v155, v118
	v_fma_f32 v118, v133, s42, -v151
	v_exp_f32_e32 v163, v118
	v_fma_f32 v118, v134, s42, -v151
	v_exp_f32_e32 v143, v118
	v_fma_f32 v118, v135, s42, -v151
	v_add_u32_e32 v178, v157, v168
	v_exp_f32_e32 v161, v118
	v_fma_f32 v118, v128, s42, -v151
	ds_read_b128 v[132:135], v178 offset:17408
	v_exp_f32_e32 v141, v118
	v_fma_f32 v118, v129, s42, -v151
	v_fma_f32 v137, v139, s42, -v150
	v_exp_f32_e32 v159, v118
	v_fma_f32 v118, v130, s42, -v151
	v_exp_f32_e32 v156, v137
	v_exp_f32_e32 v137, v118
	v_fma_f32 v118, v131, s42, -v151
	v_exp_f32_e32 v136, v136
	v_exp_f32_e32 v157, v118
	ds_read_b128 v[200:203], v178 offset:19712
	ds_read_b128 v[204:207], v178 offset:17472
	v_cvt_pk_bf16_f32 v174, v154, v162
	v_cvt_pk_bf16_f32 v175, v142, v160
	v_cvt_pk_bf16_f32 v176, v140, v158
	v_cvt_pk_bf16_f32 v177, v136, v156
	v_cvt_pk_bf16_f32 v194, v155, v163
	v_cvt_pk_bf16_f32 v195, v143, v161
	v_cvt_pk_bf16_f32 v196, v141, v159
	v_cvt_pk_bf16_f32 v197, v137, v157
	v_exp_f32_e32 v118, v117
	v_fma_f32 v117, v119, s42, -v150
	s_waitcnt lgkmcnt(2)
	v_mfma_f32_16x16x32_bf16 v[92:95], v[132:135], v[174:177], v[92:95]
	v_exp_f32_e32 v128, v117
	v_fma_f32 v117, v124, s42, -v150
	v_exp_f32_e32 v124, v117
	v_mfma_f32_16x16x32_bf16 v[60:63], v[132:135], v[194:197], v[60:63]
	ds_read_b128 v[132:135], v178 offset:22016
	ds_read_b128 v[218:221], v178 offset:19776
	v_fma_f32 v117, v125, s42, -v150
	v_exp_f32_e32 v130, v117
	s_waitcnt lgkmcnt(3)
	v_mfma_f32_16x16x32_bf16 v[88:91], v[200:203], v[174:177], v[88:91]
	v_fma_f32 v117, v126, s42, -v150
	v_exp_f32_e32 v126, v117
	v_fma_f32 v117, v127, s42, -v150
	v_mfma_f32_16x16x32_bf16 v[56:59], v[200:203], v[194:197], v[56:59]
	ds_read_b128 v[200:203], v178 offset:24320
	ds_read_b128 v[222:225], v178 offset:22080
	v_fma_f32 v112, v112, s42, -v151
	ds_read_b128 v[226:229], v178 offset:26624
	ds_read_b128 v[230:233], v178 offset:24384
	s_waitcnt lgkmcnt(5)
	v_mfma_f32_16x16x32_bf16 v[84:87], v[132:135], v[174:177], v[84:87]
	v_fma_f32 v116, v116, s42, -v150
	v_exp_f32_e32 v116, v116
	v_cvt_pk_bf16_f32 v235, v118, v128
	v_mfma_f32_16x16x32_bf16 v[52:55], v[132:135], v[194:197], v[52:55]
	v_exp_f32_e32 v132, v117
	v_exp_f32_e32 v117, v112
	v_fma_f32 v112, v113, s42, -v151
	s_waitcnt lgkmcnt(3)
	v_mfma_f32_16x16x32_bf16 v[80:83], v[200:203], v[174:177], v[80:83]
	v_exp_f32_e32 v139, v112
	v_fma_f32 v112, v114, s42, -v151
	v_exp_f32_e32 v119, v112
	v_mfma_f32_16x16x32_bf16 v[48:51], v[200:203], v[194:197], v[48:51]
	ds_read_b128 v[200:203], v178 offset:28928
	ds_read_b128 v[238:241], v178 offset:26688
	v_fma_f32 v112, v115, s42, -v151
	v_exp_f32_e32 v129, v112
	v_fma_f32 v112, v120, s42, -v151
	s_waitcnt lgkmcnt(3)
	v_mfma_f32_16x16x32_bf16 v[76:79], v[226:229], v[174:177], v[76:79]
	v_exp_f32_e32 v125, v112
	v_fma_f32 v120, v121, s42, -v151
	v_exp_f32_e32 v131, v120
	v_mfma_f32_16x16x32_bf16 v[44:47], v[226:229], v[194:197], v[44:47]
	ds_read_b128 v[226:229], v178 offset:31232
	ds_read_b128 v[242:245], v178 offset:28992
	v_fma_f32 v120, v122, s42, -v151
	v_exp_f32_e32 v127, v120
	s_waitcnt lgkmcnt(3)
	v_mfma_f32_16x16x32_bf16 v[72:75], v[200:203], v[174:177], v[72:75]
	v_fma_f32 v120, v123, s42, -v151
	v_exp_f32_e32 v133, v120
	v_cvt_pk_bf16_f32 v234, v116, v138
	v_mfma_f32_16x16x32_bf16 v[40:43], v[200:203], v[194:197], v[40:43]
	ds_read_b128 v[200:203], v178 offset:33536
	ds_read_b128 v[246:249], v178 offset:31296
	ds_read_b128 v[112:115], v178 offset:33600
	v_cvt_pk_bf16_f32 v236, v124, v130
	s_waitcnt lgkmcnt(4)
	v_mfma_f32_16x16x32_bf16 v[68:71], v[226:229], v[174:177], v[68:71]
	v_cvt_pk_bf16_f32 v237, v126, v132
	v_cvt_pk_bf16_f32 v120, v117, v139
	v_cvt_pk_bf16_f32 v121, v119, v129
	v_mfma_f32_16x16x32_bf16 v[36:39], v[226:229], v[194:197], v[36:39]
	v_cvt_pk_bf16_f32 v122, v125, v131
	v_cvt_pk_bf16_f32 v123, v127, v133
	s_andn2_b64 vcc, exec, s[10:11]
	s_waitcnt lgkmcnt(2)
	v_mfma_f32_16x16x32_bf16 v[64:67], v[200:203], v[174:177], v[64:67]
	v_mfma_f32_16x16x32_bf16 v[32:35], v[200:203], v[194:197], v[32:35]
	v_mfma_f32_16x16x32_bf16 v[92:95], v[204:207], v[234:237], v[92:95]
	v_mfma_f32_16x16x32_bf16 v[60:63], v[204:207], v[120:123], v[60:63]
	v_mfma_f32_16x16x32_bf16 v[88:91], v[218:221], v[234:237], v[88:91]
	v_mfma_f32_16x16x32_bf16 v[56:59], v[218:221], v[120:123], v[56:59]
	v_mfma_f32_16x16x32_bf16 v[84:87], v[222:225], v[234:237], v[84:87]
	v_mfma_f32_16x16x32_bf16 v[52:55], v[222:225], v[120:123], v[52:55]
	v_mfma_f32_16x16x32_bf16 v[80:83], v[230:233], v[234:237], v[80:83]
	v_mfma_f32_16x16x32_bf16 v[48:51], v[230:233], v[120:123], v[48:51]
	v_mfma_f32_16x16x32_bf16 v[76:79], v[238:241], v[234:237], v[76:79]
	v_mfma_f32_16x16x32_bf16 v[44:47], v[238:241], v[120:123], v[44:47]
	v_mfma_f32_16x16x32_bf16 v[72:75], v[242:245], v[234:237], v[72:75]
	v_mfma_f32_16x16x32_bf16 v[40:43], v[242:245], v[120:123], v[40:43]
	s_waitcnt lgkmcnt(1)
	v_mfma_f32_16x16x32_bf16 v[68:71], v[246:249], v[234:237], v[68:71]
	v_mfma_f32_16x16x32_bf16 v[36:39], v[246:249], v[120:123], v[36:39]
	s_waitcnt lgkmcnt(0)
	v_mfma_f32_16x16x32_bf16 v[64:67], v[112:115], v[234:237], v[64:67]
	v_mfma_f32_16x16x32_bf16 v[32:35], v[112:115], v[120:123], v[32:35]
	s_cbranch_vccnz .LBB0_336
	s_xor_b32 s8, s17, 1
	s_mul_i32 s8, s8, 0x8c00
	s_add_i32 s8, s8, 16
	v_add3_u32 v112, s8, v164, v173
	s_waitcnt vmcnt(3)
	ds_write_b128 v112, v[96:99]
	s_waitcnt vmcnt(2)
	ds_write_b128 v112, v[100:103] offset:8704
	v_add3_u32 v112, s8, v165, v166
	v_xor_b32_e32 v113, 16, v166
	v_add3_u32 v113, s8, v165, v113
	s_waitcnt vmcnt(1)
	ds_write_b64 v112, v[104:105] offset:17408
	ds_write_b64 v113, v[106:107] offset:17408
	s_waitcnt vmcnt(0)
	ds_write_b64 v112, v[108:109] offset:26624
	ds_write_b64 v113, v[110:111] offset:26624
	s_branch .LBB0_336

; template <int MODE> ...
;   int tid = threadIdx.x;
;   asm volatile("" : "+v"(tid));
;   const int lane = tid & 63, c = lane & 15, quad = lane >> 4;
;   float m_run[2] = {-1e30f, -1e30f}, l_run[2] = {0.f, 0.f};
; #pragma unroll
;   for (int qs = 0; qs < 2; ++qs)
; #pragma unroll
;     for (int i = 0; i < 8; ++i) o[qs][i] = (f32x4){0.f, 0.f, 0.f, 0.f};
;   const int krow0 = tid >> 4, kch = tid & 15;
;   const int vrow0 = tid >> 3, vch = tid & 7;
;   const bf16_t* kp = Kg + (size_t)(jlo * 64 + krow0) * NPAD + kch * 8;
;   const bf16_t* vp0 = VTg + (size_t)vrow0 * SEQ + jlo * 64 + vch * 8;
;   uint4 kr0 = *(const uint4*)kp, kr1 = *(const uint4*)(kp + (size_t)32 * NPAD);
;   uint4 vr0 = *(const uint4*)vp0, vr1 = *(const uint4*)(vp0 + (size_t)64 * SEQ);
;   __syncthreads();
;   stage_write_k((bf16_t*)smem, krow0, kch, kr0, kr1);
;   stage_write_v((bf16_t*)(smem + KT_BYTES), vrow0, vch, vr0, vr1);
;   __syncthreads();
; __device__ __forceinline__ void attn_phase(const bf16_t* __restrict__ proj, const bf16_t* __restrict__ KC,
;                            const bf16_t* __restrict__ VCT, const bf16_t* __restrict__ VT,
;                            bf16_t* __restrict__ mixed) {
;     ...
;     bf16x8 qf[2][4];
; #pragma unroll
;     for (int qs = 0; qs < 2; ++qs) {
;       const bf16_t* qp = proj + (row0 + qs * 4) * NPAD + OFF_Q + head * 128 + quad * 8;
; #pragma unroll
;       for (int ks = 0; ks < 4; ++ks) qf[qs][ks] = *(const bf16x8*)(qp + ks * 32);
;     }
.LBB0_655:
	v_mov_b64_e32 v[0:1], s[28:29]
	v_mad_u64_u32 v[192:193], s[6:7], v184, s81, v[0:1]
	v_mad_i32_i24 v193, v185, s81, v193
	s_mul_i32 s6, s26, 0x7a00
	v_mov_b32_e32 v105, v181
	v_lshl_add_u64 v[0:1], v[192:193], 0, v[180:181]
	s_add_u32 s62, s28, s6
	v_lshl_add_u64 v[16:17], v[0:1], 0, v[104:105]
	s_addc_u32 s63, s29, 0
	s_lshl_b32 s7, s71, 8
	v_add_co_u32_e32 v8, vcc, s19, v16
	s_add_u32 s8, s62, s7
	s_nop 0
	v_addc_co_u32_e32 v9, vcc, 0, v17, vcc
	s_addc_u32 s9, s63, 0
	v_add_co_u32_e32 v24, vcc, s85, v16
	s_add_u32 s8, s8, 0x5800
	v_lshl_add_u64 v[12:13], v[16:17], 0, s[42:43]
	v_lshl_add_u64 v[28:29], v[16:17], 0, s[46:47]
	v_addc_co_u32_e32 v25, vcc, 0, v17, vcc
	s_addc_u32 s9, s9, 0
	s_lshl_b32 s10, s95, 20
	v_mov_b32_e32 v39, v254
	global_load_dwordx4 v[0:3], v[12:13], off offset:64
	global_load_dwordx4 v[4:7], v[12:13], off offset:128
	s_nop 0
	global_load_dwordx4 v[8:11], v[8:9], off
	s_nop 0
	global_load_dwordx4 v[12:15], v[12:13], off offset:192
	s_nop 0
	global_load_dwordx4 v[16:19], v[28:29], off offset:64
	global_load_dwordx4 v[20:23], v[28:29], off offset:128
	s_nop 0
	global_load_dwordx4 v[24:27], v[24:25], off offset:2048
	s_nop 0
	global_load_dwordx4 v[28:31], v[28:29], off offset:192
	s_and_b32 s10, s10, 0x700000
	v_mov_b64_e32 v[32:33], s[8:9]
	v_and_b32_e32 v172, 15, v39
	v_ashrrev_i32_e32 v38, 4, v39
	v_ashrrev_i32_e32 v56, 3, v39
	s_add_u32 s14, s75, s10
	v_mad_i64_i32 v[34:35], s[8:9], v38, s81, v[32:33]
	v_lshlrev_b32_e32 v32, 4, v172
	v_mov_b32_e32 v33, v181
	v_ashrrev_i32_e32 v57, 31, v56
	s_addc_u32 s15, s76, 0
	v_and_b32_e32 v36, 7, v39
	v_lshl_add_u64 v[48:49], v[34:35], 0, v[32:33]
	v_lshlrev_b64 v[34:35], 13, v[56:57]
	v_lshl_add_u64 v[40:41], s[14:15], 0, v[34:35]
	v_lshlrev_b32_e32 v36, 4, v36
	v_mov_b32_e32 v37, v181
	v_lshl_add_u64 v[52:53], v[40:41], 0, v[36:37]
	global_load_dwordx4 v[40:43], v[52:53], off
	global_load_dwordx4 v[44:47], v[48:49], off
	v_add_co_u32_e32 v48, vcc, s89, v48
	v_bfe_u32 v166, v39, 4, 2
	s_nop 0
	v_addc_co_u32_e32 v49, vcc, 0, v49, vcc
	global_load_dwordx4 v[48:51], v[48:49], off
	v_add_co_u32_e32 v52, vcc, s88, v52
	v_lshlrev_b32_e32 v57, 3, v39
	s_nop 0
	v_addc_co_u32_e32 v53, vcc, 0, v53, vcc
	global_load_dwordx4 v[52:55], v[52:53], off
	v_lshlrev_b32_e32 v58, 4, v39
	v_lshlrev_b32_e32 v39, 1, v39
	v_and_b32_e32 v57, 32, v57
	v_and_b32_e32 v58, 16, v58
	v_and_b32_e32 v39, 4, v39
	v_mul_lo_u32 v59, v38, s86
	v_mul_lo_u32 v56, v56, s87
	v_or3_b32 v39, v57, v58, v39
	v_lshlrev_b32_e32 v168, 1, v59
	v_lshlrev_b32_e32 v169, 1, v56
	v_lshlrev_b32_e32 v170, 1, v39
	v_lshrrev_b32_e32 v58, 5, v254
	v_lshrrev_b32_e32 v59, 6, v254
	v_xor_b32_e32 v58, v58, v59
	v_and_b32_e32 v58, 1, v58
	v_lshlrev_b32_e32 v58, 4, v58
	v_add_u32_e32 v170, v170, v58
	v_add3_u32 v56, 16, v168, v32
	v_lshrrev_b32_e32 v58, 6, v254
	v_lshrrev_b32_e32 v59, 7, v254
	v_xor_b32_e32 v58, v58, v59
	v_and_b32_e32 v58, 1, v58
	v_bfe_u32 v59, v254, 0, 1
	v_and_b32_e32 v59, v59, v58
	v_lshlrev_b32_e32 v58, 4, v58
	v_lshlrev_b32_e32 v59, 5, v59
	v_sub_u32_e32 v58, v58, v59
	v_add_u32_e32 v56, v56, v58
	v_add3_u32 v39, 16, v169, v170
	v_xor_b32_e32 v59, 16, v170
	v_add3_u32 v58, 16, v169, v59
	s_cmp_lg_u32 s96, 0
	v_lshlrev_b32_e32 v167, 4, v166
	v_add_u32_e32 v57, 0x4000, v39
	v_add_u32_e32 v39, 0x6800, v39
	s_barrier
	s_waitcnt vmcnt(1)
	ds_write_b128 v56, v[48:51] offset:8704
	ds_write_b128 v56, v[44:47]
	ds_write_b64 v57, v[40:41] offset:1024
	ds_write_b64 v58, v[42:43] offset:17408
	s_waitcnt vmcnt(0)
	ds_write_b64 v39, v[52:53]
	ds_write_b64 v58, v[54:55] offset:26624
	s_waitcnt lgkmcnt(0)
	s_barrier
	s_cbranch_scc0 .LBB0_663
	s_add_u32 s6, s7, s6
	v_mad_i64_i32 v[38:39], s[8:9], v38, s81, 0
	s_addc_u32 s7, 0, 0
	v_lshl_add_u64 v[38:39], s[6:7], 0, v[38:39]
	s_and_b32 s6, s95, 7
	s_lshl_b32 s26, s6, 20
	v_lshlrev_b32_e32 v40, 3, v172
	v_lshl_add_u64 v[144:145], v[38:39], 0, v[32:33]
	v_lshl_add_u64 v[32:33], s[26:27], 0, v[34:35]
	v_mov_b32_e32 v34, v181
	v_mov_b32_e32 v35, v181
	v_lshl_add_u64 v[146:147], v[32:33], 0, v[36:37]
	v_mov_b32_e32 v32, v181
	v_mov_b32_e32 v33, v181
	v_mov_b32_e32 v164, 0xf149f2ca
	v_lshlrev_b32_e32 v175, 1, v40
	v_lshrrev_b32_e32 v96, 6, v254
	v_lshrrev_b32_e32 v97, 7, v254
	v_xor_b32_e32 v96, v96, v97
	v_and_b32_e32 v96, 1, v96
	v_bfe_u32 v97, v254, 0, 1
	v_and_b32_e32 v97, v97, v96
	v_lshlrev_b32_e32 v96, 4, v96
	v_lshlrev_b32_e32 v97, 5, v97
	v_sub_u32_e32 v96, v96, v97
	v_add_u32_e32 v175, v175, v96
	v_mov_b64_e32 v[42:43], v[34:35]
	v_mov_b64_e32 v[50:51], v[34:35]
	v_mov_b64_e32 v[58:59], v[34:35]
	v_mov_b64_e32 v[66:67], v[34:35]
	v_mov_b64_e32 v[74:75], v[34:35]
	v_mov_b64_e32 v[82:83], v[34:35]
	v_mov_b64_e32 v[90:91], v[34:35]
	v_mov_b64_e32 v[38:39], v[34:35]
	v_mov_b64_e32 v[46:47], v[34:35]
	v_mov_b64_e32 v[54:55], v[34:35]
	v_mov_b64_e32 v[62:63], v[34:35]
	v_mov_b64_e32 v[70:71], v[34:35]
	v_mov_b64_e32 v[78:79], v[34:35]
	v_mov_b64_e32 v[86:87], v[34:35]
	v_mov_b64_e32 v[94:95], v[34:35]
	v_mul_u32_u24_e32 v171, 0x110, v172
	v_mul_u32_u24_e32 v173, 0x90, v172
	v_add_u32_e32 v174, 16, v167
	v_lshrrev_b32_e32 v96, 2, v254
	v_lshrrev_b32_e32 v97, 3, v254
	v_xor_b32_e32 v96, v96, v97
	v_and_b32_e32 v96, 1, v96
	v_bfe_u32 v97, v254, 4, 1
	v_and_b32_e32 v97, v97, v96
	v_lshlrev_b32_e32 v96, 4, v96
	v_lshlrev_b32_e32 v97, 5, v97
	v_sub_u32_e32 v96, v96, v97
	v_add_u32_e32 v174, v174, v96
	v_mov_b32_e32 v194, v181
	v_mov_b32_e32 v195, v181
	s_mov_b64 s[60:61], 0
	v_mov_b64_e32 v[40:41], v[32:33]
	v_mov_b64_e32 v[48:49], v[32:33]
	v_mov_b64_e32 v[56:57], v[32:33]
	v_mov_b64_e32 v[64:65], v[32:33]
	v_mov_b64_e32 v[72:73], v[32:33]
	v_mov_b64_e32 v[80:81], v[32:33]
	v_mov_b64_e32 v[88:89], v[32:33]
	v_mov_b64_e32 v[36:37], v[32:33]
	v_mov_b64_e32 v[44:45], v[32:33]
	v_mov_b64_e32 v[52:53], v[32:33]
	v_mov_b64_e32 v[60:61], v[32:33]
	v_mov_b64_e32 v[68:69], v[32:33]
	v_mov_b64_e32 v[76:77], v[32:33]
	v_mov_b64_e32 v[84:85], v[32:33]
	v_mov_b64_e32 v[92:93], v[32:33]
	v_mov_b32_e32 v165, v164
	v_lshl_add_u64 v[144:145], s[24:25], 0, v[144:145]
	v_lshl_add_u64 v[146:147], s[24:25], 0, v[146:147]
	v_add_co_u32_e32 v144, vcc, s90, v144
	s_nop 1
	v_addc_co_u32_e32 v145, vcc, 0, v145, vcc
	v_add_co_u32_e32 v146, vcc, 0x3a800000, v146
	s_nop 1
	v_addc_co_u32_e32 v147, vcc, 0, v147, vcc
	s_branch .LBB0_659

; __device__ __forceinline__ void stage_write_v(bf16_t* Vt, int vrow0, int vch, uint4 vr0, uint4 vr1) {
;   const int g4a = 2 * vch, g4b = 2 * vch + 1;
;   const int pa = (g4a >> 3) * 32 + (g4a & 3) * 8 + ((g4a >> 2) & 1) * 4;
;   const int pb = (g4b >> 3) * 32 + (g4b & 3) * 8 + ((g4b >> 2) & 1) * 4;
;   *(uint2*)(Vt + vrow0 * VT_STRIDE + pa) = make_uint2(vr0.x, vr0.y);
;   *(uint2*)(Vt + vrow0 * VT_STRIDE + pb) = make_uint2(vr0.z, vr0.w);
;   *(uint2*)(Vt + (vrow0 + 64) * VT_STRIDE + pa) = make_uint2(vr1.x, vr1.y);
;   *(uint2*)(Vt + (vrow0 + 64) * VT_STRIDE + pb) = make_uint2(vr1.z, vr1.w);
; }
; template <int MODE> ...
;     ...
;     if (j < jhi) {
;       stage_write_k((bf16_t*)(smem + (cb ^ 1) * STAGE_BYTES), krow0, kch, kr0, kr1);
;       stage_write_v((bf16_t*)(smem + (cb ^ 1) * STAGE_BYTES + KT_BYTES), vrow0, vch, vr0, vr1);
;     }
;     __syncthreads();
.LBB0_658:
	s_xor_b32 s6, s8, 1
	s_mul_i32 s6, s6, 0x8c00
	s_add_i32 s6, s6, 16
	v_add3_u32 v112, s6, v168, v175
	s_add_u32 s60, s60, 1
	s_waitcnt vmcnt(3)
	ds_write_b128 v112, v[96:99]
	s_waitcnt vmcnt(2)
	ds_write_b128 v112, v[100:103] offset:8704
	v_add3_u32 v96, s6, v169, v170
	s_addc_u32 s61, s61, 0
	v_xor_b32_e32 v97, 16, v170
	v_add3_u32 v97, s6, v169, v97
	v_lshl_add_u64 v[144:145], v[144:145], 0, s[50:51]
	s_cmp_eq_u32 s96, s60
	v_lshl_add_u64 v[146:147], v[146:147], 0, s[52:53]
	s_waitcnt vmcnt(1)
	ds_write_b64 v96, v[104:105] offset:17408
	ds_write_b64 v97, v[106:107] offset:17408
	s_waitcnt vmcnt(0)
	ds_write_b64 v96, v[108:109] offset:26624
	ds_write_b64 v97, v[110:111] offset:26624
	s_waitcnt lgkmcnt(0)
	s_barrier
	s_cbranch_scc1 .LBB0_662

; template <int MODE> ...
;     ...
;     if (MODE == 0) need = (wunion >> j) & 1ull;
;     if (need) {
;       f32x4 s[2][4];
; #pragma unroll
;       for (int mt = 0; mt < 4; ++mt) {
;         s[0][mt] = (f32x4){0.f, 0.f, 0.f, 0.f};
;         s[1][mt] = (f32x4){0.f, 0.f, 0.f, 0.f};
;       }
; #pragma unroll
;       for (int ks = 0; ks < 4; ++ks)
; #pragma unroll
;         for (int mt = 0; mt < 4; ++mt) {
;           bf16x8 a = *(const bf16x8*)(Kt + (mt * 16 + c) * KT_STRIDE + ks * 32 + quad * 8);
;           s[0][mt] = __builtin_amdgcn_mfma_f32_16x16x32_bf16(a, qf[0][ks], s[0][mt], 0, 0, 0);
;           s[1][mt] = __builtin_amdgcn_mfma_f32_16x16x32_bf16(a, qf[1][ks], s[1][mt], 0, 0, 0);
;         }
;       const bool edge = (j == jhi) || (MODE == 1 && j == jhi - 8);
;       bf16x8 pb[2][2];
;       if (edge) {
; #pragma unroll
;         for (int qs = 0; qs < 2; ++qs) {
;           const int key0 = j * 64 + quad * 4;
;           const int tk = tok[qs];
; #pragma unroll
;           for (int mt = 0; mt < 4; ++mt)
; #pragma unroll
;             for (int jj = 0; jj < 4; ++jj) {
;               const int key = key0 + mt * 16 + jj;
;               bool valid = key <= tk;
;               if (MODE == 1) valid = valid && (key > tk - 512);
;               s[qs][mt][jj] = valid ? s[qs][mt][jj] : RAW_MASKED;
;             }
;         }
;       }
;       float alpha[2];
; #pragma unroll
;       for (int qs = 0; qs < 2; ++qs) {
;         const bool sel = (MODE == 1) ? true : (bool)((mymask[qs] >> j) & 1ull);
;         float mx4[4];
; #pragma unroll
;         for (int mt = 0; mt < 4; ++mt)
;           mx4[mt] = fmaxf(fmaxf(s[qs][mt][0], s[qs][mt][1]), fmaxf(s[qs][mt][2], s[qs][mt][3]));
;         float mx = fmaxf(fmaxf(mx4[0], mx4[1]), fmaxf(mx4[2], mx4[3]));
;         mx = sel ? mx * SCL : -1e30f;
;         mx = quad_max(mx);
.LBB0_666:
	s_lshl_b64 s[6:7], 1, s96
	s_and_b64 s[8:9], s[16:17], s[6:7]
	s_cmp_lg_u64 s[8:9], 0
	v_or_b32_e32 v198, 4, v186
	s_cbranch_scc0 .LBB0_681
	s_bitcmp1_b32 s96, 0
	s_cselect_b32 s8, 0x8c00, 0
	s_add_i32 s8, s8, 16
	v_add_u32_e32 v173, s8, v167
	v_lshrrev_b32_e32 v230, 2, v254
	v_lshrrev_b32_e32 v231, 3, v254
	v_xor_b32_e32 v230, v230, v231
	v_and_b32_e32 v230, 1, v230
	v_bfe_u32 v231, v254, 4, 1
	v_and_b32_e32 v231, v231, v230
	v_lshlrev_b32_e32 v230, 4, v230
	v_lshlrev_b32_e32 v231, 5, v231
	v_sub_u32_e32 v230, v230, v231
	v_add_u32_e32 v173, v173, v230
	v_mad_u32_u24 v167, v172, s78, v173
	ds_read_b128 v[168:171], v167
	ds_read_b128 v[230:233], v167 offset:64
	ds_read_b128 v[200:203], v167 offset:4352
	ds_read_b128 v[208:211], v167 offset:8704
	ds_read_b128 v[222:225], v167 offset:13056
	v_and_b32_e32 v163, s7, v163
	v_and_b32_e32 v162, s6, v162
	v_cmp_eq_u64_e64 s[10:11], 0, v[162:163]
	v_and_b32_e32 v161, s7, v161
	s_waitcnt lgkmcnt(4)
	v_mfma_f32_16x16x32_bf16 v[174:177], v[168:171], v[8:11], 0
	v_and_b32_e32 v160, s6, v160
	v_cmp_eq_u64_e64 s[6:7], 0, v[160:161]
	v_mfma_f32_16x16x32_bf16 v[168:171], v[168:171], v[24:27], 0
	s_waitcnt lgkmcnt(3)
	v_mfma_f32_16x16x32_bf16 v[174:177], v[230:233], v[0:3], v[174:177]
	v_mfma_f32_16x16x32_bf16 v[168:171], v[230:233], v[16:19], v[168:171]
	ds_read_b128 v[230:233], v167 offset:4416
	s_waitcnt lgkmcnt(3)
	v_mfma_f32_16x16x32_bf16 v[204:207], v[200:203], v[8:11], 0
	v_mfma_f32_16x16x32_bf16 v[200:203], v[200:203], v[24:27], 0
	s_waitcnt lgkmcnt(0)
	v_mfma_f32_16x16x32_bf16 v[204:207], v[230:233], v[0:3], v[204:207]
	v_mfma_f32_16x16x32_bf16 v[200:203], v[230:233], v[16:19], v[200:203]
	ds_read_b128 v[230:233], v167 offset:8768
	v_mfma_f32_16x16x32_bf16 v[218:221], v[208:211], v[8:11], 0
	v_mfma_f32_16x16x32_bf16 v[208:211], v[208:211], v[24:27], 0
	s_waitcnt lgkmcnt(0)
	v_mfma_f32_16x16x32_bf16 v[218:221], v[230:233], v[0:3], v[218:221]
	v_mfma_f32_16x16x32_bf16 v[208:211], v[230:233], v[16:19], v[208:211]
	ds_read_b128 v[230:233], v167 offset:13120
	v_mfma_f32_16x16x32_bf16 v[226:229], v[222:225], v[8:11], 0
	v_mfma_f32_16x16x32_bf16 v[222:225], v[222:225], v[24:27], 0
	s_waitcnt lgkmcnt(0)
	v_mfma_f32_16x16x32_bf16 v[226:229], v[230:233], v[0:3], v[226:229]
	v_mfma_f32_16x16x32_bf16 v[222:225], v[230:233], v[16:19], v[222:225]
	ds_read_b128 v[230:233], v167 offset:128
	s_waitcnt lgkmcnt(0)
	v_mfma_f32_16x16x32_bf16 v[174:177], v[230:233], v[4:7], v[174:177]
	v_mfma_f32_16x16x32_bf16 v[168:171], v[230:233], v[20:23], v[168:171]
	ds_read_b128 v[230:233], v167 offset:4480
	s_waitcnt lgkmcnt(0)
	v_mfma_f32_16x16x32_bf16 v[204:207], v[230:233], v[4:7], v[204:207]
	v_mfma_f32_16x16x32_bf16 v[200:203], v[230:233], v[20:23], v[200:203]
	ds_read_b128 v[230:233], v167 offset:8832
	s_waitcnt lgkmcnt(0)
	v_mfma_f32_16x16x32_bf16 v[218:221], v[230:233], v[4:7], v[218:221]
	v_mfma_f32_16x16x32_bf16 v[208:211], v[230:233], v[20:23], v[208:211]
	ds_read_b128 v[230:233], v167 offset:13184
	s_waitcnt lgkmcnt(0)
	v_mfma_f32_16x16x32_bf16 v[226:229], v[230:233], v[4:7], v[226:229]
	v_mfma_f32_16x16x32_bf16 v[222:225], v[230:233], v[20:23], v[222:225]
	ds_read_b128 v[230:233], v167 offset:192
	s_waitcnt lgkmcnt(0)
	v_mfma_f32_16x16x32_bf16 v[174:177], v[230:233], v[12:15], v[174:177]
	v_mfma_f32_16x16x32_bf16 v[230:233], v[230:233], v[28:31], v[168:171]
	s_nop 2
	ds_read_b128 v[168:171], v167 offset:4544
	s_waitcnt lgkmcnt(0)
	v_mfma_f32_16x16x32_bf16 v[204:207], v[168:171], v[12:15], v[204:207]
	v_mfma_f32_16x16x32_bf16 v[234:237], v[168:171], v[28:31], v[200:203]
	ds_read_b128 v[168:171], v167 offset:8896
	s_waitcnt lgkmcnt(0)
	v_mfma_f32_16x16x32_bf16 v[218:221], v[168:171], v[12:15], v[218:221]
	v_mfma_f32_16x16x32_bf16 v[208:211], v[168:171], v[28:31], v[208:211]
	ds_read_b128 v[168:171], v167 offset:13248
	v_lshl_or_b32 v167, v166, 2, s97
	v_cmp_le_i32_e32 vcc, v167, v186
	s_waitcnt lgkmcnt(0)
	v_mfma_f32_16x16x32_bf16 v[226:229], v[168:171], v[12:15], v[226:229]
	v_or_b32_e32 v178, 18, v167
	v_or_b32_e32 v179, 19, v167
	v_or_b32_e32 v183, 32, v167
	v_mfma_f32_16x16x32_bf16 v[238:241], v[168:171], v[28:31], v[222:225]
	v_cndmask_b32_e32 v168, v216, v174, vcc
	v_cmp_lt_i32_e32 vcc, v167, v186
	v_or_b32_e32 v174, 2, v167
	v_or_b32_e32 v191, 33, v167
	v_cndmask_b32_e32 v169, v216, v175, vcc
	v_cmp_le_i32_e32 vcc, v174, v186
	v_or_b32_e32 v175, 3, v167
	v_or_b32_e32 v196, 34, v167
	v_cndmask_b32_e32 v170, v216, v176, vcc
	v_cmp_le_i32_e32 vcc, v175, v186
	v_or_b32_e32 v176, 16, v167
	v_or_b32_e32 v197, 35, v167
	v_cndmask_b32_e32 v171, v216, v177, vcc
	v_cmp_le_i32_e32 vcc, v176, v186
	v_or_b32_e32 v177, 17, v167
	v_or_b32_e32 v199, 48, v167
	v_cndmask_b32_e32 v203, v216, v204, vcc
	v_cmp_le_i32_e32 vcc, v177, v186
	v_or_b32_e32 v200, 49, v167
	v_or_b32_e32 v201, 50, v167
	v_cndmask_b32_e32 v204, v216, v205, vcc
	v_cmp_le_i32_e32 vcc, v178, v186
	v_or_b32_e32 v202, 51, v167
	s_nop 0
	v_cndmask_b32_e32 v205, v216, v206, vcc
	v_cmp_le_i32_e32 vcc, v179, v186
	s_nop 1
	v_cndmask_b32_e32 v206, v216, v207, vcc
	v_cmp_le_i32_e32 vcc, v183, v186
	s_nop 1
	v_cndmask_b32_e32 v207, v216, v218, vcc
	v_cmp_le_i32_e32 vcc, v191, v186
	s_nop 1
	v_cndmask_b32_e32 v217, v216, v219, vcc
	v_cmp_le_i32_e32 vcc, v196, v186
	s_nop 1
	v_cndmask_b32_e32 v218, v216, v220, vcc
	v_cmp_le_i32_e32 vcc, v197, v186
	v_max_f32_e32 v224, v218, v218
	s_nop 0
	v_cndmask_b32_e32 v219, v216, v221, vcc
	v_cmp_le_i32_e32 vcc, v199, v186
	s_nop 1
	v_cndmask_b32_e32 v220, v216, v226, vcc
	v_cmp_le_i32_e32 vcc, v200, v186
	s_nop 1
	v_cndmask_b32_e32 v221, v216, v227, vcc
	v_cmp_le_i32_e32 vcc, v201, v186
	s_nop 1
	v_cndmask_b32_e32 v222, v216, v228, vcc
; template <int MODE> ...
;     ...
;       const bool edge = (j == jhi) || (MODE == 1 && j == jhi - 8);
;       bf16x8 pb[2][2];
;       if (edge) {
; #pragma unroll
;         for (int qs = 0; qs < 2; ++qs) {
;           const int key0 = j * 64 + quad * 4;
;           const int tk = tok[qs];
; #pragma unroll
;           for (int mt = 0; mt < 4; ++mt)
; #pragma unroll
;             for (int jj = 0; jj < 4; ++jj) {
;               const int key = key0 + mt * 16 + jj;
;               bool valid = key <= tk;
;               if (MODE == 1) valid = valid && (key > tk - 512);
;               s[qs][mt][jj] = valid ? s[qs][mt][jj] : RAW_MASKED;
;             }
;         }
;       }
;       float alpha[2];
; #pragma unroll
;       for (int qs = 0; qs < 2; ++qs) {
;         const bool sel = (MODE == 1) ? true : (bool)((mymask[qs] >> j) & 1ull);
;         float mx4[4];
; #pragma unroll
;         for (int mt = 0; mt < 4; ++mt)
;           mx4[mt] = fmaxf(fmaxf(s[qs][mt][0], s[qs][mt][1]), fmaxf(s[qs][mt][2], s[qs][mt][3]));
;         float mx = fmaxf(fmaxf(mx4[0], mx4[1]), fmaxf(mx4[2], mx4[3]));
;         mx = sel ? mx * SCL : -1e30f;
;         mx = quad_max(mx);
;         const float m_new = (mx > m_run[qs] + RESCALE_THR) ? mx : m_run[qs];
;         alpha[qs] = __builtin_amdgcn_exp2f(m_run[qs] - m_new);
;         m_run[qs] = m_new;
;         const float negm = sel ? -m_new : -1e30f;
;         float ps4[4];
; #pragma unroll
;         for (int mt = 0; mt < 4; ++mt) {
; #pragma unroll
;           for (int jj = 0; jj < 4; ++jj) s[qs][mt][jj] = __builtin_amdgcn_exp2f(fmaf(s[qs][mt][jj], SCL, negm));
;           ps4[mt] = (s[qs][mt][0] + s[qs][mt][1]) + (s[qs][mt][2] + s[qs][mt][3]);
;         }
;         l_run[qs] = l_run[qs] * alpha[qs] + ((ps4[0] + ps4[1]) + (ps4[2] + ps4[3]));
; #pragma unroll
;         for (int kk = 0; kk < 2; ++kk) {
;           uint4 pk;
;           pk.x = pack2(s[qs][2 * kk][0], s[qs][2 * kk][1]);
;           pk.y = pack2(s[qs][2 * kk][2], s[qs][2 * kk][3]);
;           pk.z = pack2(s[qs][2 * kk + 1][0], s[qs][2 * kk + 1][1]);
;           pk.w = pack2(s[qs][2 * kk + 1][2], s[qs][2 * kk + 1][3]);
;           pb[qs][kk] = *reinterpret_cast<bf16x8*>(&pk);
;         }
;       }
;       if (__ballot(alpha[0] != 1.0f || alpha[1] != 1.0f) != 0ull) {
; #pragma unroll
;         for (int qs = 0; qs < 2; ++qs)
; #pragma unroll
	v_cmp_le_i32_e32 vcc, v202, v186
	v_max_f32_e32 v225, v222, v222
	s_nop 0
	v_cndmask_b32_e32 v223, v216, v229, vcc
	v_cmp_le_i32_e32 vcc, v167, v198
	s_nop 1
	v_cndmask_b32_e32 v166, v216, v230, vcc
	v_cmp_lt_i32_e32 vcc, v167, v198
	s_nop 1
	v_cndmask_b32_e32 v167, v216, v231, vcc
	v_cmp_le_i32_e32 vcc, v174, v198
	s_nop 1
	v_cndmask_b32_e32 v174, v216, v232, vcc
	v_cmp_le_i32_e32 vcc, v175, v198
	s_nop 1
	v_cndmask_b32_e32 v175, v216, v233, vcc
	v_cmp_le_i32_e32 vcc, v176, v198
	s_nop 1
	v_cndmask_b32_e32 v176, v216, v234, vcc
	v_cmp_le_i32_e32 vcc, v177, v198
	s_nop 1
	v_cndmask_b32_e32 v177, v216, v235, vcc
	v_cmp_le_i32_e32 vcc, v178, v198
	s_nop 1
	v_cndmask_b32_e32 v178, v216, v236, vcc
	v_cmp_le_i32_e32 vcc, v179, v198
	s_nop 1
	v_cndmask_b32_e32 v179, v216, v237, vcc
	v_cmp_le_i32_e32 vcc, v183, v198
	s_nop 1
	v_cndmask_b32_e32 v183, v216, v208, vcc
	v_cmp_le_i32_e32 vcc, v191, v198
	v_max_f32_e32 v208, v171, v171
	s_nop 0
	v_cndmask_b32_e32 v191, v216, v209, vcc
	v_cmp_le_i32_e32 vcc, v196, v198
	v_max_f32_e32 v209, v170, v170
	v_max_f32_e32 v208, v209, v208
	v_cndmask_b32_e32 v196, v216, v210, vcc
	v_cmp_le_i32_e32 vcc, v197, v198
	v_max_f32_e32 v209, v206, v206
	v_max_f32_e32 v210, v205, v205
	v_cndmask_b32_e32 v197, v216, v211, vcc
	v_max_f32_e32 v209, v210, v209
	v_max_f32_e32 v210, v217, v217
	v_max_f32_e32 v211, v207, v207
	v_max_f32_e32 v210, v211, v210
	v_max_f32_e32 v211, v219, v219
	v_max_f32_e32 v211, v224, v211
	v_max_f32_e32 v224, v223, v223
	v_max_f32_e32 v224, v225, v224
	v_max3_f32 v224, v220, v221, v224
	v_max3_f32 v208, v168, v169, v208
	v_max3_f32 v209, v203, v204, v209
	v_max3_f32 v162, v210, v211, v224
	v_max3_f32 v162, v208, v209, v162
	v_mul_f32_e32 v162, 0x3e0293ee, v162
	v_cndmask_b32_e64 v162, v162, v214, s[10:11]
	v_mov_b32_e32 v163, v162
	s_nop 1
	v_permlane16_swap_b32_e32 v162, v163
	v_max_f32_e32 v163, v163, v163
	v_max_f32_e32 v162, v162, v162
	v_max_f32_e32 v162, v162, v163
	v_cmp_le_i32_e32 vcc, v199, v198
	v_mov_b32_e32 v163, v162
	s_nop 1
	v_permlane32_swap_b32_e32 v162, v163
	v_cndmask_b32_e32 v199, v216, v238, vcc
	v_cmp_le_i32_e32 vcc, v200, v198
	v_max_f32_e32 v163, v163, v163
	v_max_f32_e32 v162, v162, v162
	v_cndmask_b32_e32 v200, v216, v239, vcc
	v_cmp_le_i32_e32 vcc, v201, v198
	v_max_f32_e32 v162, v162, v163
	v_add_f32_e32 v163, 0x41000000, v164
	v_cndmask_b32_e32 v201, v216, v240, vcc
	v_cmp_le_i32_e32 vcc, v202, v198
	v_max_f32_e32 v208, v174, v174
	v_max_f32_e32 v209, v178, v178
	v_cndmask_b32_e32 v202, v216, v241, vcc
	v_cmp_gt_f32_e32 vcc, v162, v163
	v_max_f32_e32 v210, v183, v183
	v_max_f32_e32 v211, v196, v196
	v_cndmask_b32_e32 v162, v164, v162, vcc
	v_sub_f32_e32 v163, v164, v162
	v_exp_f32_e32 v164, v163
	v_max_f32_e32 v163, v175, v175
	v_max_f32_e32 v163, v208, v163
	v_max_f32_e32 v208, v179, v179
	v_max_f32_e32 v208, v209, v208
	v_max_f32_e32 v209, v191, v191
	v_max_f32_e32 v209, v210, v209
	v_max_f32_e32 v210, v197, v197
	v_max_f32_e32 v210, v211, v210
	v_max_f32_e32 v211, v202, v202
	v_max_f32_e32 v224, v201, v201
	v_max_f32_e32 v211, v224, v211
	v_max3_f32 v211, v199, v200, v211
	v_max3_f32 v163, v166, v167, v163
	v_max3_f32 v208, v176, v177, v208
	v_max3_f32 v160, v209, v210, v211
	v_max3_f32 v160, v163, v208, v160
	v_mul_f32_e32 v160, 0x3e0293ee, v160
	v_cndmask_b32_e64 v160, v160, v214, s[6:7]
	v_mov_b32_e32 v161, v160
	s_nop 1
	v_permlane16_swap_b32_e32 v160, v161
	v_max_f32_e32 v161, v161, v161
	v_max_f32_e32 v160, v160, v160
	v_max_f32_e32 v160, v160, v161
	v_mov_b32_e32 v161, v160
	s_nop 1
	v_permlane32_swap_b32_e32 v160, v161
	v_max_f32_e32 v161, v161, v161
	v_max_f32_e32 v160, v160, v160
	v_max_f32_e32 v160, v160, v161
	v_add_f32_e32 v161, 0x41000000, v165
	v_cmp_gt_f32_e32 vcc, v160, v161
	s_nop 1
	v_cndmask_b32_e32 v224, v165, v160, vcc
	v_sub_f32_e32 v160, v165, v224
	v_exp_f32_e32 v165, v160
	v_cmp_neq_f32_e32 vcc, 1.0, v164
	v_cmp_neq_f32_e64 s[12:13], 1.0, v165
	s_or_b64 vcc, vcc, s[12:13]
	s_cbranch_vccz .LBB0_669
	v_mov_b32_e32 v160, v165
	v_pk_mul_f32 v[156:157], v[156:157], v[164:165] op_sel_hi:[1,0]
	v_pk_mul_f32 v[158:159], v[158:159], v[164:165] op_sel_hi:[1,0]
	v_pk_mul_f32 v[148:149], v[148:149], v[164:165] op_sel_hi:[1,0]
	v_pk_mul_f32 v[150:151], v[150:151], v[164:165] op_sel_hi:[1,0]
	v_pk_mul_f32 v[144:145], v[144:145], v[164:165] op_sel_hi:[1,0]
	v_pk_mul_f32 v[146:147], v[146:147], v[164:165] op_sel_hi:[1,0]
	v_pk_mul_f32 v[140:141], v[140:141], v[164:165] op_sel_hi:[1,0]
	v_pk_mul_f32 v[142:143], v[142:143], v[164:165] op_sel_hi:[1,0]
	v_pk_mul_f32 v[136:137], v[136:137], v[164:165] op_sel_hi:[1,0]
	v_pk_mul_f32 v[138:139], v[138:139], v[164:165] op_sel_hi:[1,0]
	v_pk_mul_f32 v[128:129], v[128:129], v[164:165] op_sel_hi:[1,0]
	v_pk_mul_f32 v[130:131], v[130:131], v[164:165] op_sel_hi:[1,0]
	v_pk_mul_f32 v[120:121], v[120:121], v[164:165] op_sel_hi:[1,0]
	v_pk_mul_f32 v[122:123], v[122:123], v[164:165] op_sel_hi:[1,0]
	v_pk_mul_f32 v[112:113], v[112:113], v[164:165] op_sel_hi:[1,0]
	v_pk_mul_f32 v[114:115], v[114:115], v[164:165] op_sel_hi:[1,0]
	v_pk_mul_f32 v[154:155], v[154:155], v[160:161] op_sel_hi:[1,0]
	v_pk_mul_f32 v[152:153], v[152:153], v[160:161] op_sel_hi:[1,0]
	v_pk_mul_f32 v[134:135], v[134:135], v[160:161] op_sel_hi:[1,0]
	v_pk_mul_f32 v[132:133], v[132:133], v[160:161] op_sel_hi:[1,0]
	v_pk_mul_f32 v[126:127], v[126:127], v[160:161] op_sel_hi:[1,0]
	v_pk_mul_f32 v[124:125], v[124:125], v[160:161] op_sel_hi:[1,0]
	v_pk_mul_f32 v[118:119], v[118:119], v[160:161] op_sel_hi:[1,0]
	v_pk_mul_f32 v[116:117], v[116:117], v[160:161] op_sel_hi:[1,0]
	v_pk_mul_f32 v[110:111], v[110:111], v[160:161] op_sel_hi:[1,0]
	v_pk_mul_f32 v[108:109], v[108:109], v[160:161] op_sel_hi:[1,0]
	v_pk_mul_f32 v[106:107], v[106:107], v[160:161] op_sel_hi:[1,0]
	v_pk_mul_f32 v[104:105], v[104:105], v[160:161] op_sel_hi:[1,0]
	v_pk_mul_f32 v[102:103], v[102:103], v[160:161] op_sel_hi:[1,0]
	v_pk_mul_f32 v[100:101], v[100:101], v[160:161] op_sel_hi:[1,0]
	v_pk_mul_f32 v[98:99], v[98:99], v[160:161] op_sel_hi:[1,0]
	v_pk_mul_f32 v[96:97], v[96:97], v[160:161] op_sel_hi:[1,0]

; __device__ __forceinline__ float bf2f(unsigned short h) { return __uint_as_float(((unsigned)h) << 16); }
; __device__ __forceinline__ float bflo(unsigned u) { return __uint_as_float(u << 16); }
; __device__ __forceinline__ float bfhi(unsigned u) { return __uint_as_float(u & 0xffff0000u); }
; __device__ __forceinline__ float sigmoid_f(float z) { return 1.0f / (1.0f + __expf(-z)); }
; template <int MODE> ...
;     ...
; #pragma unroll
;   for (int qs = 0; qs < 2; ++qs) {
;     float l = l_run[qs];
;     l = quad_sum(l);
;     l_out[qs] = l;
;   }
; __device__ __forceinline__ void attn_phase(const bf16_t* __restrict__ proj, const bf16_t* __restrict__ KC,
;                            const bf16_t* __restrict__ VCT, const bf16_t* __restrict__ VT,
;                            bf16_t* __restrict__ mixed) {
;     ...
;       for (int qs = 0; qs < 2; ++qs) {
;         const float g1 = sigmoid_f(bf2f(proj[(row0 + qs * 4) * NPAD + OFF_G + head * 3 + 1])) / l[qs];
; #pragma unroll
;         for (int dt = 0; dt < 8; ++dt) {
;           uint2 pv = oacc[((w * 2 + qs) * 8 + dt) * 64 + lane];
;           uint2 ov;
;           ov.x = pack2(bflo(pv.x) + g1 * o[qs][dt][0], bfhi(pv.x) + g1 * o[qs][dt][1]);
;           ov.y = pack2(bflo(pv.y) + g1 * o[qs][dt][2], bfhi(pv.y) + g1 * o[qs][dt][3]);
;           oacc[((w * 2 + qs) * 8 + dt) * 64 + lane] = ov;
;         }
;       }
.LBB0_671:
	v_mad_u64_u32 v[32:33], s[6:7], v184, s81, 0
	v_mov_b32_e32 v191, v181
	v_mad_i32_i24 v33, v185, s81, v33
	v_lshl_add_u64 v[34:35], s[28:29], 0, v[190:191]
	v_lshl_add_u64 v[48:49], v[34:35], 0, v[32:33]
	v_add_co_u32_e32 v32, vcc, s84, v48
	s_nop 1
	v_addc_co_u32_e32 v33, vcc, 0, v49, vcc
	s_barrier
	global_load_ushort v50, v[32:33], off offset:2050
	v_mov_b32_e32 v52, v197
	v_add_co_u32_e32 v48, vcc, s92, v48
	s_nop 0
	v_permlane16_swap_b32_e32 v197, v52
	v_addc_co_u32_e32 v49, vcc, 0, v49, vcc
	ds_read2st64_b64 v[32:35], v187 offset1:1
	ds_read2st64_b64 v[36:39], v187 offset0:2 offset1:3
	ds_read2st64_b64 v[40:43], v187 offset0:4 offset1:5
	ds_read2st64_b64 v[44:47], v187 offset0:6 offset1:7
	v_add_f32_e32 v53, v197, v52
	global_load_ushort v52, v[48:49], off offset:2
	v_mov_b32_e32 v51, v196
	s_nop 1
	v_permlane16_swap_b32_e32 v196, v51
	v_add_f32_e32 v51, v196, v51
	v_mov_b32_e32 v183, v51
	s_nop 1
	v_permlane32_swap_b32_e32 v51, v183
	s_waitcnt lgkmcnt(3)
	v_lshlrev_b32_e32 v48, 16, v32
	v_and_b32_e32 v49, 0xffff0000, v32
	v_lshlrev_b32_e32 v32, 16, v33
	v_and_b32_e32 v33, 0xffff0000, v33
	v_lshlrev_b32_e32 v54, 16, v34
	v_and_b32_e32 v55, 0xffff0000, v34
	v_lshlrev_b32_e32 v34, 16, v35
	v_and_b32_e32 v35, 0xffff0000, v35
	s_waitcnt lgkmcnt(2)
	v_lshlrev_b32_e32 v56, 16, v36
	v_and_b32_e32 v57, 0xffff0000, v36
	v_lshlrev_b32_e32 v36, 16, v37
	v_and_b32_e32 v37, 0xffff0000, v37
	v_lshlrev_b32_e32 v58, 16, v38
	v_and_b32_e32 v59, 0xffff0000, v38
	v_lshlrev_b32_e32 v38, 16, v39
	v_and_b32_e32 v39, 0xffff0000, v39
	s_waitcnt lgkmcnt(1)
	v_lshlrev_b32_e32 v60, 16, v40
	v_and_b32_e32 v61, 0xffff0000, v40
	v_lshlrev_b32_e32 v40, 16, v41
	v_and_b32_e32 v41, 0xffff0000, v41
	v_lshlrev_b32_e32 v62, 16, v42
	v_and_b32_e32 v63, 0xffff0000, v42
	v_lshlrev_b32_e32 v42, 16, v43
	v_and_b32_e32 v43, 0xffff0000, v43
	v_mov_b32_e32 v64, v53
	s_nop 1
	v_permlane32_swap_b32_e32 v53, v64
	v_add_u32_e32 v169, 0xfffffe00, v186
	v_add_u32_e32 v170, 0xfffffe04, v186
	s_waitcnt vmcnt(1)
	v_lshlrev_b32_e32 v50, 16, v50
	v_mul_f32_e32 v50, 0xbfb8aa3b, v50
	v_exp_f32_e32 v50, v50
	s_nop 0
	v_pk_add_f32 v[50:51], v[50:51], v[182:183]
	s_nop 0
	v_div_scale_f32 v65, s[6:7], v50, v50, 1.0
	v_rcp_f32_e32 v66, v65
	v_div_scale_f32 v67, vcc, 1.0, v50, 1.0
	v_mov_b32_e32 v183, v64
	v_fma_f32 v68, -v65, v66, 1.0
	v_fmac_f32_e32 v66, v68, v66
	v_mul_f32_e32 v68, v67, v66
	v_fma_f32 v69, -v65, v68, v67
	v_fmac_f32_e32 v68, v69, v66
	v_fma_f32 v65, -v65, v68, v67
	v_div_fmas_f32 v65, v65, v66, v68
	v_div_fixup_f32 v50, v65, v50, 1.0
	v_div_scale_f32 v65, s[6:7], v51, v51, v50
	v_rcp_f32_e32 v66, v65
	v_div_scale_f32 v67, vcc, v50, v51, v50
	v_fma_f32 v68, -v65, v66, 1.0
	v_fmac_f32_e32 v66, v68, v66
	v_mul_f32_e32 v68, v67, v66
	v_fma_f32 v69, -v65, v68, v67
	v_fmac_f32_e32 v68, v69, v66
	v_fma_f32 v65, -v65, v68, v67
	v_div_fmas_f32 v65, v65, v66, v68
	v_div_fixup_f32 v50, v65, v51, v50
	v_pk_fma_f32 v[48:49], v[124:125], v[50:51], v[48:49] op_sel_hi:[1,0,1]
	v_pk_fma_f32 v[32:33], v[126:127], v[50:51], v[32:33] op_sel_hi:[1,0,1]
	v_pk_fma_f32 v[54:55], v[128:129], v[50:51], v[54:55] op_sel_hi:[1,0,1]
	v_pk_fma_f32 v[34:35], v[130:131], v[50:51], v[34:35] op_sel_hi:[1,0,1]
	v_pk_fma_f32 v[56:57], v[132:133], v[50:51], v[56:57] op_sel_hi:[1,0,1]
	v_pk_fma_f32 v[36:37], v[134:135], v[50:51], v[36:37] op_sel_hi:[1,0,1]
	v_pk_fma_f32 v[58:59], v[136:137], v[50:51], v[58:59] op_sel_hi:[1,0,1]
	v_pk_fma_f32 v[38:39], v[138:139], v[50:51], v[38:39] op_sel_hi:[1,0,1]
	v_pk_fma_f32 v[60:61], v[144:145], v[50:51], v[60:61] op_sel_hi:[1,0,1]
	v_pk_fma_f32 v[40:41], v[146:147], v[50:51], v[40:41] op_sel_hi:[1,0,1]
	v_pk_fma_f32 v[62:63], v[148:149], v[50:51], v[62:63] op_sel_hi:[1,0,1]
	v_pk_fma_f32 v[42:43], v[150:151], v[50:51], v[42:43] op_sel_hi:[1,0,1]
	v_cvt_pk_bf16_f32 v48, v48, v49
	v_cvt_pk_bf16_f32 v49, v32, v33
	v_cvt_pk_bf16_f32 v32, v54, v55
	v_cvt_pk_bf16_f32 v33, v34, v35
	v_cvt_pk_bf16_f32 v34, v56, v57
	v_cvt_pk_bf16_f32 v35, v36, v37
	v_cvt_pk_bf16_f32 v36, v58, v59
	v_cvt_pk_bf16_f32 v37, v38, v39
	v_cvt_pk_bf16_f32 v38, v60, v61
	v_cvt_pk_bf16_f32 v39, v40, v41
	v_cvt_pk_bf16_f32 v40, v62, v63
	v_cvt_pk_bf16_f32 v41, v42, v43
	ds_write2st64_b64 v187, v[48:49], v[32:33] offset1:1
	ds_write2st64_b64 v187, v[34:35], v[36:37] offset0:2 offset1:3
	ds_write2st64_b64 v187, v[38:39], v[40:41] offset0:4 offset1:5
	s_waitcnt lgkmcnt(3)
	v_lshlrev_b32_e32 v32, 16, v44
	v_and_b32_e32 v33, 0xffff0000, v44
	v_lshlrev_b32_e32 v34, 16, v45
	v_and_b32_e32 v35, 0xffff0000, v45
	v_pk_fma_f32 v[32:33], v[152:153], v[50:51], v[32:33] op_sel_hi:[1,0,1]
	v_pk_fma_f32 v[34:35], v[154:155], v[50:51], v[34:35] op_sel_hi:[1,0,1]
	v_cvt_pk_bf16_f32 v32, v32, v33
	v_cvt_pk_bf16_f32 v33, v34, v35
	s_waitcnt vmcnt(0)
	v_lshlrev_b32_e32 v35, 16, v52
	v_mul_f32_e32 v35, 0xbfb8aa3b, v35
	v_exp_f32_e32 v52, v35
	v_lshlrev_b32_e32 v34, 16, v46
	v_and_b32_e32 v35, 0xffff0000, v46
	v_pk_fma_f32 v[34:35], v[156:157], v[50:51], v[34:35] op_sel_hi:[1,0,1]
	v_pk_add_f32 v[36:37], v[52:53], v[182:183]
	v_cvt_pk_bf16_f32 v34, v34, v35
	v_div_scale_f32 v40, s[6:7], v36, v36, 1.0
	v_rcp_f32_e32 v41, v40
	v_lshlrev_b32_e32 v38, 16, v47
	v_and_b32_e32 v39, 0xffff0000, v47
	v_pk_fma_f32 v[38:39], v[158:159], v[50:51], v[38:39] op_sel_hi:[1,0,1]
	v_fma_f32 v35, -v40, v41, 1.0
	v_fmac_f32_e32 v41, v35, v41
	v_div_scale_f32 v35, vcc, 1.0, v36, 1.0
	v_mul_f32_e32 v42, v35, v41
	v_fma_f32 v43, -v40, v42, v35
	v_fmac_f32_e32 v42, v43, v41
	v_fma_f32 v35, -v40, v42, v35
	v_div_fmas_f32 v35, v35, v41, v42
	v_div_fixup_f32 v36, v35, v36, 1.0
	v_div_scale_f32 v40, s[6:7], v37, v37, v36
	v_rcp_f32_e32 v41, v40
	v_cvt_pk_bf16_f32 v35, v38, v39
	ds_write2st64_b64 v187, v[32:33], v[34:35] offset0:6 offset1:7
	s_lshl_b32 s6, s8, 1
	v_fma_f32 v32, -v40, v41, 1.0
	v_fmac_f32_e32 v41, v32, v41
	v_div_scale_f32 v32, vcc, v36, v37, v36
	v_mul_f32_e32 v38, v32, v41
	v_fma_f32 v33, -v40, v38, v32
	v_fmac_f32_e32 v38, v33, v41
	v_fma_f32 v39, -v40, v38, v32
	ds_read2st64_b64 v[32:35], v187 offset0:8 offset1:9
	v_div_fmas_f32 v38, v39, v41, v38
	v_div_fixup_f32 v40, v38, v37, v36
	ds_read2st64_b64 v[36:39], v187 offset0:10 offset1:11
	s_add_u32 s6, s62, s6
	s_waitcnt lgkmcnt(1)
; __device__ __forceinline__ float bflo(unsigned u) { return __uint_as_float(u << 16); }
; __device__ __forceinline__ float bfhi(unsigned u) { return __uint_as_float(u & 0xffff0000u); }
; template <int MODE> ...
;     ...
;   const int krow0 = tid >> 4, kch = tid & 15;
;   const int vrow0 = tid >> 3, vch = tid & 7;
;   const bf16_t* kp = Kg + (size_t)(jlo * 64 + krow0) * NPAD + kch * 8;
;   const bf16_t* vp0 = VTg + (size_t)vrow0 * SEQ + jlo * 64 + vch * 8;
;   uint4 kr0 = *(const uint4*)kp, kr1 = *(const uint4*)(kp + (size_t)32 * NPAD);
;   uint4 vr0 = *(const uint4*)vp0, vr1 = *(const uint4*)(vp0 + (size_t)64 * SEQ);
;   __syncthreads();
;   stage_write_k((bf16_t*)smem, krow0, kch, kr0, kr1);
;   stage_write_v((bf16_t*)(smem + KT_BYTES), vrow0, vch, vr0, vr1);
; __device__ __forceinline__ void attn_phase(const bf16_t* __restrict__ proj, const bf16_t* __restrict__ KC,
;                            const bf16_t* __restrict__ VCT, const bf16_t* __restrict__ VT,
;                            bf16_t* __restrict__ mixed) {
;     ...
; #pragma unroll
;         for (int dt = 0; dt < 8; ++dt) {
;           uint2 pv = oacc[((w * 2 + qs) * 8 + dt) * 64 + lane];
;           uint2 ov;
;           ov.x = pack2(bflo(pv.x) + g1 * o[qs][dt][0], bfhi(pv.x) + g1 * o[qs][dt][1]);
;           ov.y = pack2(bflo(pv.y) + g1 * o[qs][dt][2], bfhi(pv.y) + g1 * o[qs][dt][3]);
;           oacc[((w * 2 + qs) * 8 + dt) * 64 + lane] = ov;
;         }
;       }
	v_lshlrev_b32_e32 v42, 16, v32
	v_and_b32_e32 v43, 0xffff0000, v32
	v_pk_fma_f32 v[42:43], v[96:97], v[40:41], v[42:43] op_sel_hi:[1,0,1]
	s_addc_u32 s7, s63, 0
	v_cvt_pk_bf16_f32 v32, v42, v43
	v_lshlrev_b32_e32 v42, 16, v33
	v_and_b32_e32 v43, 0xffff0000, v33
	v_pk_fma_f32 v[42:43], v[98:99], v[40:41], v[42:43] op_sel_hi:[1,0,1]
	s_add_u32 s6, s6, 0x6000
	v_cvt_pk_bf16_f32 v33, v42, v43
	v_lshlrev_b32_e32 v42, 16, v34
	v_and_b32_e32 v43, 0xffff0000, v34
	v_pk_fma_f32 v[42:43], v[100:101], v[40:41], v[42:43] op_sel_hi:[1,0,1]
	s_addc_u32 s7, s7, 0
	v_cvt_pk_bf16_f32 v34, v42, v43
	v_lshlrev_b32_e32 v42, 16, v35
	v_and_b32_e32 v43, 0xffff0000, v35
	v_pk_fma_f32 v[42:43], v[102:103], v[40:41], v[42:43] op_sel_hi:[1,0,1]
	v_mov_b32_e32 v144, 0
	v_cvt_pk_bf16_f32 v35, v42, v43
	ds_write2st64_b64 v187, v[32:33], v[34:35] offset0:8 offset1:9
	s_waitcnt lgkmcnt(1)
	v_lshlrev_b32_e32 v32, 16, v36
	v_and_b32_e32 v33, 0xffff0000, v36
	v_pk_fma_f32 v[32:33], v[108:109], v[40:41], v[32:33] op_sel_hi:[1,0,1]
	v_lshlrev_b32_e32 v42, 16, v39
	v_cvt_pk_bf16_f32 v36, v32, v33
	v_lshlrev_b32_e32 v32, 16, v37
	v_and_b32_e32 v33, 0xffff0000, v37
	v_pk_fma_f32 v[32:33], v[110:111], v[40:41], v[32:33] op_sel_hi:[1,0,1]
	v_and_b32_e32 v43, 0xffff0000, v39
	v_cvt_pk_bf16_f32 v37, v32, v33
	v_lshlrev_b32_e32 v32, 16, v38
	v_and_b32_e32 v33, 0xffff0000, v38
	v_pk_fma_f32 v[32:33], v[112:113], v[40:41], v[32:33] op_sel_hi:[1,0,1]
	v_pk_fma_f32 v[42:43], v[114:115], v[40:41], v[42:43] op_sel_hi:[1,0,1]
	v_cvt_pk_bf16_f32 v38, v32, v33
	ds_read2st64_b64 v[32:35], v187 offset0:12 offset1:13
	v_cvt_pk_bf16_f32 v39, v42, v43
	ds_write2st64_b64 v187, v[36:37], v[38:39] offset0:10 offset1:11
	ds_read2st64_b64 v[36:39], v187 offset0:14 offset1:15
	v_mov_b32_e32 v150, 0xf149f2ca
	s_waitcnt lgkmcnt(2)
	v_lshlrev_b32_e32 v42, 16, v32
	v_and_b32_e32 v43, 0xffff0000, v32
	v_pk_fma_f32 v[42:43], v[104:105], v[40:41], v[42:43] op_sel_hi:[1,0,1]
	s_mov_b32 s8, 0
	v_cvt_pk_bf16_f32 v32, v42, v43
	v_lshlrev_b32_e32 v42, 16, v33
	v_and_b32_e32 v43, 0xffff0000, v33
	v_pk_fma_f32 v[42:43], v[106:107], v[40:41], v[42:43] op_sel_hi:[1,0,1]
	v_mov_b32_e32 v151, v150
	v_cvt_pk_bf16_f32 v33, v42, v43
	v_lshlrev_b32_e32 v42, 16, v34
	v_and_b32_e32 v43, 0xffff0000, v34
	v_pk_fma_f32 v[42:43], v[116:117], v[40:41], v[42:43] op_sel_hi:[1,0,1]
	v_mov_b32_e32 v145, v144
	v_cvt_pk_bf16_f32 v34, v42, v43
	v_lshlrev_b32_e32 v42, 16, v35
	v_and_b32_e32 v43, 0xffff0000, v35
	v_pk_fma_f32 v[42:43], v[118:119], v[40:41], v[42:43] op_sel_hi:[1,0,1]
	s_nop 0
	v_cvt_pk_bf16_f32 v35, v42, v43
	ds_write2st64_b64 v187, v[32:33], v[34:35] offset0:12 offset1:13
	s_waitcnt lgkmcnt(1)
	v_lshlrev_b32_e32 v32, 16, v36
	v_and_b32_e32 v33, 0xffff0000, v36
	v_lshlrev_b32_e32 v34, 16, v37
	v_and_b32_e32 v35, 0xffff0000, v37
	v_pk_fma_f32 v[32:33], v[120:121], v[40:41], v[32:33] op_sel_hi:[1,0,1]
	v_pk_fma_f32 v[34:35], v[122:123], v[40:41], v[34:35] op_sel_hi:[1,0,1]
	v_cvt_pk_bf16_f32 v32, v32, v33
	v_cvt_pk_bf16_f32 v33, v34, v35
	v_lshlrev_b32_e32 v34, 16, v38
	v_and_b32_e32 v35, 0xffff0000, v38
	v_lshlrev_b32_e32 v36, 16, v39
	v_and_b32_e32 v37, 0xffff0000, v39
	v_pk_fma_f32 v[34:35], v[140:141], v[40:41], v[34:35] op_sel_hi:[1,0,1]
	v_pk_fma_f32 v[36:37], v[142:143], v[40:41], v[36:37] op_sel_hi:[1,0,1]
	v_cvt_pk_bf16_f32 v34, v34, v35
	v_cvt_pk_bf16_f32 v35, v36, v37
	v_mov_b32_e32 v43, v254
	ds_write2st64_b64 v187, v[32:33], v[34:35] offset0:14 offset1:15
	v_sub_u32_e64 v42, s96, 8 clamp
	v_mov_b64_e32 v[34:35], s[6:7]
	v_ashrrev_i32_e32 v45, 4, v43
	v_and_b32_e32 v44, 15, v43
	v_ashrrev_i32_e32 v32, 3, v43
	v_lshl_add_u32 v33, v42, 6, v45
	v_mad_i64_i32 v[34:35], s[6:7], v33, s81, v[34:35]
	v_lshlrev_b32_e32 v36, 4, v44
	v_mov_b32_e32 v37, v181
	v_ashrrev_i32_e32 v33, 31, v32
	v_lshl_add_u64 v[146:147], v[34:35], 0, v[36:37]
	v_lshlrev_b64 v[34:35], 13, v[32:33]
	v_and_b32_e32 v46, 7, v43
	v_lshl_add_u64 v[34:35], s[14:15], 0, v[34:35]
	v_lshlrev_b32_e32 v38, 7, v42
	v_mov_b32_e32 v39, v181
	v_add_co_u32_e32 v40, vcc, s89, v146
	global_load_dwordx4 v[96:99], v[146:147], off
	s_nop 0
	v_addc_co_u32_e32 v41, vcc, 0, v147, vcc
	v_lshl_add_u64 v[34:35], v[34:35], 0, v[38:39]
	v_lshlrev_b32_e32 v38, 4, v46
	global_load_dwordx4 v[100:103], v[40:41], off
	v_lshl_add_u64 v[34:35], v[34:35], 0, v[38:39]
	v_add_co_u32_e32 v38, vcc, s93, v34
	v_lshl_add_u64 v[148:149], v[34:35], 0, s[54:55]
	s_nop 0
	v_addc_co_u32_e32 v39, vcc, 0, v35, vcc
	global_load_dwordx4 v[104:107], v[38:39], off
	v_add_co_u32_e32 v38, vcc, s94, v34
	v_mul_lo_u32 v34, v45, s86
	s_nop 0
	v_addc_co_u32_e32 v39, vcc, 0, v35, vcc
	global_load_dwordx4 v[108:111], v[38:39], off
	v_lshlrev_b32_e32 v164, 1, v34
	v_add3_u32 v34, 16, v164, v36
	v_lshrrev_b32_e32 v167, 6, v254
	v_lshrrev_b32_e32 v168, 7, v254
	v_xor_b32_e32 v167, v167, v168
	v_and_b32_e32 v167, 1, v167
	v_bfe_u32 v168, v254, 0, 1
	v_and_b32_e32 v168, v168, v167
	v_lshlrev_b32_e32 v167, 4, v167
	v_lshlrev_b32_e32 v168, 5, v168
	v_sub_u32_e32 v167, v167, v168
	v_add_u32_e32 v34, v34, v167
	v_lshlrev_b32_e32 v33, 3, v43
	s_waitcnt lgkmcnt(0)
	s_barrier
; __device__ __forceinline__ void stage_write_v(bf16_t* Vt, int vrow0, int vch, uint4 vr0, uint4 vr1) {
;   const int g4a = 2 * vch, g4b = 2 * vch + 1;
;   const int pa = (g4a >> 3) * 32 + (g4a & 3) * 8 + ((g4a >> 2) & 1) * 4;
;   const int pb = (g4b >> 3) * 32 + (g4b & 3) * 8 + ((g4b >> 2) & 1) * 4;
;   *(uint2*)(Vt + vrow0 * VT_STRIDE + pa) = make_uint2(vr0.x, vr0.y);
;   *(uint2*)(Vt + vrow0 * VT_STRIDE + pb) = make_uint2(vr0.z, vr0.w);
;   *(uint2*)(Vt + (vrow0 + 64) * VT_STRIDE + pa) = make_uint2(vr1.x, vr1.y);
;   *(uint2*)(Vt + (vrow0 + 64) * VT_STRIDE + pb) = make_uint2(vr1.z, vr1.w);
; }
; template <int MODE> ...
;   int tid = threadIdx.x;
;   asm volatile("" : "+v"(tid));
;   const int lane = tid & 63, c = lane & 15, quad = lane >> 4;
;   float m_run[2] = {-1e30f, -1e30f}, l_run[2] = {0.f, 0.f};
; #pragma unroll
;   for (int qs = 0; qs < 2; ++qs)
; #pragma unroll
;     for (int i = 0; i < 8; ++i) o[qs][i] = (f32x4){0.f, 0.f, 0.f, 0.f};
;   const int krow0 = tid >> 4, kch = tid & 15;
;   const int vrow0 = tid >> 3, vch = tid & 7;
;   const bf16_t* kp = Kg + (size_t)(jlo * 64 + krow0) * NPAD + kch * 8;
;   const bf16_t* vp0 = VTg + (size_t)vrow0 * SEQ + jlo * 64 + vch * 8;
;   uint4 kr0 = *(const uint4*)kp, kr1 = *(const uint4*)(kp + (size_t)32 * NPAD);
;   uint4 vr0 = *(const uint4*)vp0, vr1 = *(const uint4*)(vp0 + (size_t)64 * SEQ);
;   __syncthreads();
;   stage_write_k((bf16_t*)smem, krow0, kch, kr0, kr1);
;   stage_write_v((bf16_t*)(smem + KT_BYTES), vrow0, vch, vr0, vr1);
;   __syncthreads();
	s_waitcnt vmcnt(3)
	ds_write_b128 v34, v[96:99]
	s_waitcnt vmcnt(2)
	ds_write_b128 v34, v[100:103] offset:8704
	v_lshlrev_b32_e32 v34, 4, v43
	v_lshlrev_b32_e32 v35, 1, v43
	v_and_b32_e32 v33, 32, v33
	v_and_b32_e32 v34, 16, v34
	v_and_b32_e32 v35, 4, v35
	v_or3_b32 v33, v33, v34, v35
	v_mul_lo_u32 v32, v32, s87
	v_lshlrev_b32_e32 v165, 1, v32
	v_lshlrev_b32_e32 v166, 1, v33
	v_lshrrev_b32_e32 v167, 5, v254
	v_lshrrev_b32_e32 v168, 6, v254
	v_xor_b32_e32 v167, v167, v168
	v_and_b32_e32 v167, 1, v167
	v_lshlrev_b32_e32 v167, 4, v167
	v_add_u32_e32 v166, v166, v167
	v_add3_u32 v32, 16, v165, v166
	v_xor_b32_e32 v167, 16, v166
	v_add3_u32 v168, 16, v165, v167
	v_add_u32_e32 v33, 0x4000, v32
	v_add_u32_e32 v32, 0x6800, v32
	s_min_u32 s6, s96, 8
	s_waitcnt vmcnt(0)
	ds_write_b64 v32, v[108:109]
	ds_write_b64 v168, v[110:111] offset:26624
	v_bfe_u32 v32, v43, 4, 2
	v_lshlrev_b32_e32 v37, 3, v44
	v_lshl_add_u32 v171, v32, 4, 16
	v_lshrrev_b32_e32 v172, 2, v254
	v_lshrrev_b32_e32 v173, 3, v254
	v_xor_b32_e32 v172, v172, v173
	v_and_b32_e32 v172, 1, v172
	v_bfe_u32 v173, v254, 4, 1
	v_and_b32_e32 v173, v173, v172
	v_lshlrev_b32_e32 v172, 4, v172
	v_lshlrev_b32_e32 v173, 5, v173
	v_sub_u32_e32 v172, v172, v173
	v_add_u32_e32 v171, v171, v172
	v_lshl_add_u32 v32, v32, 2, s97
	s_lshl_b32 s12, s6, 6
	v_mov_b32_e32 v34, v181
	v_mov_b32_e32 v35, v181
	v_readfirstlane_b32 s9, v42
	ds_write_b64 v33, v[104:105] offset:1024
	ds_write_b64 v168, v[106:107] offset:17408
	v_mul_u32_u24_e32 v167, 0x110, v44
	v_mul_u32_u24_e32 v168, 0x90, v44
	v_subrev_u32_e32 v172, s12, v32
	v_mov_b32_e32 v32, v181
	v_mov_b32_e32 v33, v181
	v_lshlrev_b32_e32 v173, 1, v37
	v_lshrrev_b32_e32 v36, 6, v254
	v_lshrrev_b32_e32 v37, 7, v254
	v_xor_b32_e32 v36, v36, v37
	v_and_b32_e32 v36, 1, v36
	v_bfe_u32 v37, v254, 0, 1
	v_and_b32_e32 v37, v37, v36
	v_lshlrev_b32_e32 v36, 4, v36
	v_lshlrev_b32_e32 v37, 5, v37
	v_sub_u32_e32 v36, v36, v37
	v_add_u32_e32 v173, v173, v36
	v_mov_b64_e32 v[38:39], v[34:35]
	v_mov_b64_e32 v[42:43], v[34:35]
	v_mov_b64_e32 v[46:47], v[34:35]
	v_mov_b64_e32 v[50:51], v[34:35]
	v_mov_b64_e32 v[54:55], v[34:35]
	v_mov_b64_e32 v[58:59], v[34:35]
	v_mov_b64_e32 v[62:63], v[34:35]
	v_mov_b64_e32 v[66:67], v[34:35]
	v_mov_b64_e32 v[70:71], v[34:35]
	v_mov_b64_e32 v[74:75], v[34:35]
	v_mov_b64_e32 v[78:79], v[34:35]
	v_mov_b64_e32 v[82:83], v[34:35]
	v_mov_b64_e32 v[86:87], v[34:35]
	v_mov_b64_e32 v[90:91], v[34:35]
	v_mov_b64_e32 v[94:95], v[34:35]
	s_add_i32 s13, s12, 0xfffffe00
	s_mov_b32 s14, 0
	v_mov_b64_e32 v[36:37], v[32:33]
	v_mov_b64_e32 v[40:41], v[32:33]
	v_mov_b64_e32 v[44:45], v[32:33]
	v_mov_b64_e32 v[48:49], v[32:33]
	v_mov_b64_e32 v[52:53], v[32:33]
	v_mov_b64_e32 v[56:57], v[32:33]
	v_mov_b64_e32 v[60:61], v[32:33]
	v_mov_b64_e32 v[64:65], v[32:33]
	v_mov_b64_e32 v[68:69], v[32:33]
	v_mov_b64_e32 v[72:73], v[32:33]
	v_mov_b64_e32 v[76:77], v[32:33]
	v_mov_b64_e32 v[80:81], v[32:33]
	v_mov_b64_e32 v[84:85], v[32:33]
	v_mov_b64_e32 v[88:89], v[32:33]
	v_mov_b64_e32 v[92:93], v[32:33]
	s_waitcnt lgkmcnt(0)
	s_barrier
	s_branch .LBB0_673

; template <int MODE> ...
;     ...
;         const float negm = sel ? -m_new : -1e30f;
;         float ps4[4];
; #pragma unroll
;         for (int mt = 0; mt < 4; ++mt) {
; #pragma unroll
;           for (int jj = 0; jj < 4; ++jj) s[qs][mt][jj] = __builtin_amdgcn_exp2f(fmaf(s[qs][mt][jj], SCL, negm));
;           ps4[mt] = (s[qs][mt][0] + s[qs][mt][1]) + (s[qs][mt][2] + s[qs][mt][3]);
;         }
;         l_run[qs] = l_run[qs] * alpha[qs] + ((ps4[0] + ps4[1]) + (ps4[2] + ps4[3]));
; #pragma unroll
;         for (int kk = 0; kk < 2; ++kk) {
;           uint4 pk;
;           pk.x = pack2(s[qs][2 * kk][0], s[qs][2 * kk][1]);
;           pk.y = pack2(s[qs][2 * kk][2], s[qs][2 * kk][3]);
;           pk.z = pack2(s[qs][2 * kk + 1][0], s[qs][2 * kk + 1][1]);
;           pk.w = pack2(s[qs][2 * kk + 1][2], s[qs][2 * kk + 1][3]);
;           pb[qs][kk] = *reinterpret_cast<bf16x8*>(&pk);
;         }
;       }
;       if (__ballot(alpha[0] != 1.0f || alpha[1] != 1.0f) != 0ull) {
; #pragma unroll
;         for (int qs = 0; qs < 2; ++qs)
; #pragma unroll
;           for (int dt = 0; dt < 8; ++dt) {
;             o[qs][dt][0] *= alpha[qs]; o[qs][dt][1] *= alpha[qs]; o[qs][dt][2] *= alpha[qs]; o[qs][dt][3] *= alpha[qs];
;           }
;       }
; #pragma unroll
;       for (int kk = 0; kk < 2; ++kk)
; #pragma unroll
;         for (int dt = 0; dt < 8; ++dt) {
;           bf16x8 a = *(const bf16x8*)(Vt + (dt * 16 + c) * VT_STRIDE + kk * 32 + quad * 8);
;           o[0][dt] = __builtin_amdgcn_mfma_f32_16x16x32_bf16(a, pb[0][kk], o[0][dt], 0, 0, 0);
;           o[1][dt] = __builtin_amdgcn_mfma_f32_16x16x32_bf16(a, pb[1][kk], o[1][dt], 0, 0, 0);
;         }
;     }
;     if (j < jhi) {
;       stage_write_k((bf16_t*)(smem + (cb ^ 1) * STAGE_BYTES), krow0, kch, kr0, kr1);
;       stage_write_v((bf16_t*)(smem + (cb ^ 1) * STAGE_BYTES + KT_BYTES), vrow0, vch, vr0, vr1);
;     }
;     __syncthreads();
.LBB0_679:
	v_fma_f32 v140, v140, s44, -v150
	v_exp_f32_e32 v154, v140
	v_fma_f32 v140, v141, s44, -v150
	v_exp_f32_e32 v162, v140
	v_fma_f32 v140, v142, s44, -v150
	v_exp_f32_e32 v142, v140
	v_fma_f32 v140, v143, s44, -v150
	v_fma_f32 v136, v136, s44, -v150
	v_exp_f32_e32 v160, v140
	v_exp_f32_e32 v140, v136
	v_fma_f32 v136, v137, s44, -v150
	v_fma_f32 v125, v125, s44, -v150
	v_exp_f32_e32 v158, v136
	v_fma_f32 v136, v138, s44, -v150
	v_exp_f32_e32 v138, v125
	v_fma_f32 v125, v126, s44, -v150
	v_fma_f32 v126, v132, s44, -v151
	v_exp_f32_e32 v155, v126
	v_fma_f32 v126, v133, s44, -v151
	v_exp_f32_e32 v163, v126
	v_fma_f32 v126, v134, s44, -v151
	v_exp_f32_e32 v143, v126
	v_fma_f32 v126, v135, s44, -v151
	v_add_u32_e32 v178, v157, v168
	v_exp_f32_e32 v161, v126
	v_fma_f32 v126, v128, s44, -v151
	ds_read_b128 v[132:135], v178 offset:17408
	v_exp_f32_e32 v141, v126
	v_fma_f32 v126, v129, s44, -v151
	v_fma_f32 v137, v139, s44, -v150
	v_exp_f32_e32 v159, v126
	v_fma_f32 v126, v130, s44, -v151
	v_exp_f32_e32 v156, v137
	v_exp_f32_e32 v137, v126
	v_fma_f32 v126, v131, s44, -v151
	v_exp_f32_e32 v136, v136
	v_exp_f32_e32 v157, v126
	ds_read_b128 v[200:203], v178 offset:19712
	ds_read_b128 v[204:207], v178 offset:17472
	v_cvt_pk_bf16_f32 v174, v154, v162
	v_cvt_pk_bf16_f32 v175, v142, v160
	v_cvt_pk_bf16_f32 v176, v140, v158
	v_cvt_pk_bf16_f32 v177, v136, v156
	v_cvt_pk_bf16_f32 v194, v155, v163
	v_cvt_pk_bf16_f32 v195, v143, v161
	v_cvt_pk_bf16_f32 v196, v141, v159
	v_cvt_pk_bf16_f32 v197, v137, v157
	s_waitcnt lgkmcnt(2)
	v_mfma_f32_16x16x32_bf16 v[92:95], v[132:135], v[174:177], v[92:95]
	v_exp_f32_e32 v126, v125
	v_fma_f32 v125, v127, s44, -v150
	v_fma_f32 v112, v112, s44, -v151
	v_mfma_f32_16x16x32_bf16 v[60:63], v[132:135], v[194:197], v[60:63]
	ds_read_b128 v[132:135], v178 offset:22016
	ds_read_b128 v[208:211], v178 offset:19776
	v_exp_f32_e32 v128, v125
	v_exp_f32_e32 v125, v112
	s_waitcnt lgkmcnt(3)
	v_mfma_f32_16x16x32_bf16 v[88:91], v[200:203], v[174:177], v[88:91]
	v_fma_f32 v112, v113, s44, -v151
	v_fma_f32 v121, v121, s44, -v150
	v_exp_f32_e32 v139, v112
	v_mfma_f32_16x16x32_bf16 v[56:59], v[200:203], v[194:197], v[56:59]
	ds_read_b128 v[200:203], v178 offset:24320
	ds_read_b128 v[218:221], v178 offset:22080
	ds_read_b128 v[222:225], v178 offset:26624
	ds_read_b128 v[226:229], v178 offset:24384
	v_fma_f32 v112, v114, s44, -v151
	s_waitcnt lgkmcnt(3)
	v_mfma_f32_16x16x32_bf16 v[80:83], v[200:203], v[174:177], v[80:83]
	v_exp_f32_e32 v130, v121
	v_fma_f32 v121, v122, s44, -v150
	v_exp_f32_e32 v127, v112
	v_mfma_f32_16x16x32_bf16 v[48:51], v[200:203], v[194:197], v[48:51]
	ds_read_b128 v[200:203], v178 offset:28928
	ds_read_b128 v[234:237], v178 offset:26688
	v_fma_f32 v112, v115, s44, -v151
	v_exp_f32_e32 v122, v121
	v_fma_f32 v121, v123, s44, -v150
	v_exp_f32_e32 v129, v112
	v_fma_f32 v112, v116, s44, -v151
	v_mfma_f32_16x16x32_bf16 v[84:87], v[132:135], v[174:177], v[84:87]
	v_fma_f32 v116, v117, s44, -v151
	v_exp_f32_e32 v131, v116
	v_fma_f32 v116, v118, s44, -v151
	v_mfma_f32_16x16x32_bf16 v[52:55], v[132:135], v[194:197], v[52:55]
	v_exp_f32_e32 v132, v121
	v_exp_f32_e32 v121, v112
	v_fma_f32 v124, v124, s44, -v150
	s_waitcnt lgkmcnt(3)
	v_mfma_f32_16x16x32_bf16 v[76:79], v[222:225], v[174:177], v[76:79]
	v_fma_f32 v120, v120, s44, -v150
	v_exp_f32_e32 v123, v116
	v_fma_f32 v116, v119, s44, -v151
	v_mfma_f32_16x16x32_bf16 v[44:47], v[222:225], v[194:197], v[44:47]
	ds_read_b128 v[222:225], v178 offset:31232
	ds_read_b128 v[238:241], v178 offset:28992
	v_exp_f32_e32 v124, v124
	v_exp_f32_e32 v120, v120
	s_waitcnt lgkmcnt(3)
	v_mfma_f32_16x16x32_bf16 v[72:75], v[200:203], v[174:177], v[72:75]
	v_exp_f32_e32 v133, v116
	v_cvt_pk_bf16_f32 v230, v124, v138
	v_cvt_pk_bf16_f32 v231, v126, v128
	v_mfma_f32_16x16x32_bf16 v[40:43], v[200:203], v[194:197], v[40:43]
	ds_read_b128 v[200:203], v178 offset:33536
	ds_read_b128 v[242:245], v178 offset:31296
	ds_read_b128 v[112:115], v178 offset:33600
	v_cvt_pk_bf16_f32 v232, v120, v130
	s_waitcnt lgkmcnt(4)
	v_mfma_f32_16x16x32_bf16 v[68:71], v[222:225], v[174:177], v[68:71]
	v_cvt_pk_bf16_f32 v233, v122, v132
	v_cvt_pk_bf16_f32 v116, v125, v139
	v_cvt_pk_bf16_f32 v117, v127, v129
	v_mfma_f32_16x16x32_bf16 v[36:39], v[222:225], v[194:197], v[36:39]
	v_cvt_pk_bf16_f32 v118, v121, v131
	v_cvt_pk_bf16_f32 v119, v123, v133
	s_andn2_b64 vcc, exec, s[10:11]
	s_waitcnt lgkmcnt(2)
	v_mfma_f32_16x16x32_bf16 v[64:67], v[200:203], v[174:177], v[64:67]
	v_mfma_f32_16x16x32_bf16 v[32:35], v[200:203], v[194:197], v[32:35]
	v_mfma_f32_16x16x32_bf16 v[92:95], v[204:207], v[230:233], v[92:95]
	v_mfma_f32_16x16x32_bf16 v[60:63], v[204:207], v[116:119], v[60:63]
	v_mfma_f32_16x16x32_bf16 v[88:91], v[208:211], v[230:233], v[88:91]
	v_mfma_f32_16x16x32_bf16 v[56:59], v[208:211], v[116:119], v[56:59]
	v_mfma_f32_16x16x32_bf16 v[84:87], v[218:221], v[230:233], v[84:87]
	v_mfma_f32_16x16x32_bf16 v[52:55], v[218:221], v[116:119], v[52:55]
	v_mfma_f32_16x16x32_bf16 v[80:83], v[226:229], v[230:233], v[80:83]
	v_mfma_f32_16x16x32_bf16 v[48:51], v[226:229], v[116:119], v[48:51]
	v_mfma_f32_16x16x32_bf16 v[76:79], v[234:237], v[230:233], v[76:79]
	v_mfma_f32_16x16x32_bf16 v[44:47], v[234:237], v[116:119], v[44:47]
	v_mfma_f32_16x16x32_bf16 v[72:75], v[238:241], v[230:233], v[72:75]
	v_mfma_f32_16x16x32_bf16 v[40:43], v[238:241], v[116:119], v[40:43]
	s_waitcnt lgkmcnt(1)
	v_mfma_f32_16x16x32_bf16 v[68:71], v[242:245], v[230:233], v[68:71]
	v_mfma_f32_16x16x32_bf16 v[36:39], v[242:245], v[116:119], v[36:39]
	s_waitcnt lgkmcnt(0)
	v_mfma_f32_16x16x32_bf16 v[64:67], v[112:115], v[230:233], v[64:67]
	v_mfma_f32_16x16x32_bf16 v[32:35], v[112:115], v[116:119], v[32:35]
	s_cbranch_vccnz .LBB0_672
	s_xor_b32 s6, s15, 1
	s_mul_i32 s6, s6, 0x8c00
	s_add_i32 s6, s6, 16
	v_add3_u32 v112, s6, v164, v173
	s_waitcnt vmcnt(3)
	ds_write_b128 v112, v[96:99]
	s_waitcnt vmcnt(2)
	ds_write_b128 v112, v[100:103] offset:8704
	v_add3_u32 v112, s6, v165, v166
	v_xor_b32_e32 v113, 16, v166
	v_add3_u32 v113, s6, v165, v113
	s_waitcnt vmcnt(1)
	ds_write_b64 v112, v[104:105] offset:17408
	ds_write_b64 v113, v[106:107] offset:17408
	s_waitcnt vmcnt(0)
	ds_write_b64 v112, v[108:109] offset:26624
	ds_write_b64 v113, v[110:111] offset:26624
	s_branch .LBB0_672
